# GEMM K-loop load segments: LDS-DMA loads use scalar 64-bit base + constant per-lane 32-bit offset (saddr form); the 64-bit VALU address adds are gone (derived bases formed by SALU in s98-s101), so the
# speedup vs baseline: 1.0354x; 1.0071x over previous
.LBB0_271:
	s_ashr_i32 s63, s62, 31
	s_lshl_b64 s[0:1], s[62:63], 20
	s_add_u32 s66, s49, s0
	s_addc_u32 s67, s82, s1
	s_and_b64 s[0:1], s[4:5], exec
	s_cselect_b32 s0, s67, s75
	s_cselect_b32 s1, s66, s74
	s_ashr_i32 s65, s64, 31
	s_lshl_b64 s[68:69], s[64:65], 20
	s_add_u32 s68, s45, s68
	s_addc_u32 s69, s47, s69
	s_and_b64 s[78:79], s[4:5], exec
	s_cselect_b32 s3, s69, s77
	s_cselect_b32 s63, s68, s76
	s_add_u32 s74, s74, 0x80080
	s_addc_u32 s75, s75, 0
	s_add_u32 s65, s76, 0x100
	s_addc_u32 s71, s77, 0
	s_mov_b32 s90, -2
	s_waitcnt vmcnt(0)
	ds_read_b128 v[146:149], v166
	ds_read_b128 v[150:153], v166 offset:1024
	ds_read_b128 v[154:157], v166 offset:2048
	ds_read_b128 v[170:173], v166 offset:3072
	ds_read_b128 v[174:177], v167
	ds_read_b128 v[178:181], v167 offset:1024
	ds_read_b128 v[182:185], v167 offset:2048
	ds_read_b128 v[186:189], v167 offset:3072
	s_add_u32 s76, s74, 0xfff80080
	s_addc_u32 s77, s75, -1
	s_cmp_eq_u32 s90, 28
	s_cselect_b32 s79, s0, s77
	s_cselect_b32 s78, s1, s76
	s_cselect_b32 s77, s3, s71
	s_cselect_b32 s76, s63, s65
	s_add_i32 m0, s31, 0xc000
	ds_read_b128 v[190:193], v168
	ds_read_b128 v[194:197], v168 offset:1024
	ds_read_b128 v[198:201], v168 offset:2048
	ds_read_b128 v[202:205], v168 offset:3072
	ds_read_b128 v[206:209], v168 offset:4096
	ds_read_b128 v[214:217], v168 offset:5120
	ds_read_b128 v[218:221], v168 offset:6144
	ds_read_b128 v[222:225], v168 offset:7168
	global_load_lds_dwordx4 v138, s[74:75]
	s_add_i32 m0, s31, 0xe000
	s_nop 0
	global_load_lds_dwordx4 v140, s[74:75]
	s_waitcnt vmcnt(8)
	s_waitcnt lgkmcnt(0)
	s_setprio 1
	s_barrier
	v_mfma_f32_16x16x32_bf16 v[124:127], v[146:149], v[190:193], 0
	v_mfma_f32_16x16x32_bf16 v[120:123], v[154:157], v[190:193], 0
	v_mfma_f32_16x16x32_bf16 v[108:111], v[146:149], v[198:201], 0
	v_mfma_f32_16x16x32_bf16 v[104:107], v[154:157], v[198:201], 0
	v_mfma_f32_16x16x32_bf16 v[92:95], v[146:149], v[206:209], 0
	v_mfma_f32_16x16x32_bf16 v[88:91], v[154:157], v[206:209], 0
	v_mfma_f32_16x16x32_bf16 v[76:79], v[146:149], v[218:221], 0
	v_mfma_f32_16x16x32_bf16 v[72:75], v[154:157], v[218:221], 0
	v_mfma_f32_16x16x32_bf16 v[124:127], v[150:153], v[194:197], v[124:127]
	v_mfma_f32_16x16x32_bf16 v[120:123], v[170:173], v[194:197], v[120:123]
	v_mfma_f32_16x16x32_bf16 v[108:111], v[150:153], v[202:205], v[108:111]
	v_mfma_f32_16x16x32_bf16 v[104:107], v[170:173], v[202:205], v[104:107]
	v_mfma_f32_16x16x32_bf16 v[92:95], v[150:153], v[214:217], v[92:95]
	v_mfma_f32_16x16x32_bf16 v[88:91], v[170:173], v[214:217], v[88:91]
	v_mfma_f32_16x16x32_bf16 v[76:79], v[150:153], v[222:225], v[76:79]
	v_mfma_f32_16x16x32_bf16 v[72:75], v[170:173], v[222:225], v[72:75]
	s_setprio 0
	s_setprio 1
	v_mfma_f32_16x16x32_bf16 v[116:119], v[174:177], v[190:193], 0
	v_mfma_f32_16x16x32_bf16 v[112:115], v[182:185], v[190:193], 0
	v_mfma_f32_16x16x32_bf16 v[100:103], v[174:177], v[198:201], 0
	v_mfma_f32_16x16x32_bf16 v[96:99], v[182:185], v[198:201], 0
	v_mfma_f32_16x16x32_bf16 v[84:87], v[174:177], v[206:209], 0
	v_mfma_f32_16x16x32_bf16 v[80:83], v[182:185], v[206:209], 0
	v_mfma_f32_16x16x32_bf16 v[68:71], v[174:177], v[218:221], 0
	v_mfma_f32_16x16x32_bf16 v[64:67], v[182:185], v[218:221], 0
	v_mfma_f32_16x16x32_bf16 v[116:119], v[178:181], v[194:197], v[116:119]
	v_mfma_f32_16x16x32_bf16 v[112:115], v[186:189], v[194:197], v[112:115]
	v_mfma_f32_16x16x32_bf16 v[100:103], v[178:181], v[202:205], v[100:103]
	v_mfma_f32_16x16x32_bf16 v[96:99], v[186:189], v[202:205], v[96:99]
	v_mfma_f32_16x16x32_bf16 v[84:87], v[178:181], v[214:217], v[84:87]
	v_mfma_f32_16x16x32_bf16 v[80:83], v[186:189], v[214:217], v[80:83]
	v_mfma_f32_16x16x32_bf16 v[68:71], v[178:181], v[222:225], v[68:71]
	v_mfma_f32_16x16x32_bf16 v[64:67], v[186:189], v[222:225], v[64:67]
	s_setprio 0
	s_barrier
	s_add_i32 s91, s81, s30
	s_add_u32 s98, s76, s34
	s_addc_u32 s99, s77, s35
	s_mov_b32 m0, s91
	ds_read_b128 v[190:193], v168 offset:16384
	ds_read_b128 v[194:197], v168 offset:17408
	ds_read_b128 v[198:201], v168 offset:18432
	ds_read_b128 v[202:205], v168 offset:19456
	ds_read_b128 v[206:209], v168 offset:20480
	ds_read_b128 v[214:217], v168 offset:21504
	ds_read_b128 v[218:221], v168 offset:22528
	ds_read_b128 v[222:225], v168 offset:23552
	global_load_lds_dwordx4 v130, s[76:77]
	s_add_i32 m0, s91, 0x2000
	s_add_u32 s92, s76, 0x80000
	s_addc_u32 s93, s77, 0
	s_add_i32 s91, s83, s30
	global_load_lds_dwordx4 v134, s[76:77]
	s_mov_b32 m0, s91
	s_add_u32 s100, s78, s34
	s_addc_u32 s101, s79, s35
	global_load_lds_dwordx4 v130, s[92:93]
	s_add_i32 m0, s91, 0x2000
	s_nop 0
	global_load_lds_dwordx4 v134, s[92:93]
	s_mov_b32 m0, s31
	s_nop 0
	global_load_lds_dwordx4 v128, s[78:79]
	s_mov_b32 m0, s51
	s_nop 0
	global_load_lds_dwordx4 v132, s[78:79]
	s_waitcnt vmcnt(8)
	s_waitcnt lgkmcnt(0)
	s_setprio 1
	s_barrier
	v_mfma_f32_16x16x32_bf16 v[60:63], v[146:149], v[190:193], 0
	v_mfma_f32_16x16x32_bf16 v[56:59], v[154:157], v[190:193], 0
	v_mfma_f32_16x16x32_bf16 v[44:47], v[146:149], v[198:201], 0
	v_mfma_f32_16x16x32_bf16 v[40:43], v[154:157], v[198:201], 0
	v_mfma_f32_16x16x32_bf16 v[28:31], v[146:149], v[206:209], 0
	v_mfma_f32_16x16x32_bf16 v[24:27], v[154:157], v[206:209], 0
	v_mfma_f32_16x16x32_bf16 v[12:15], v[146:149], v[218:221], 0
	v_mfma_f32_16x16x32_bf16 v[8:11], v[154:157], v[218:221], 0
	v_mfma_f32_16x16x32_bf16 v[60:63], v[150:153], v[194:197], v[60:63]
	v_mfma_f32_16x16x32_bf16 v[56:59], v[170:173], v[194:197], v[56:59]
	v_mfma_f32_16x16x32_bf16 v[44:47], v[150:153], v[202:205], v[44:47]
	v_mfma_f32_16x16x32_bf16 v[40:43], v[170:173], v[202:205], v[40:43]
	v_mfma_f32_16x16x32_bf16 v[28:31], v[150:153], v[214:217], v[28:31]
	v_mfma_f32_16x16x32_bf16 v[24:27], v[170:173], v[214:217], v[24:27]
	v_mfma_f32_16x16x32_bf16 v[12:15], v[150:153], v[222:225], v[12:15]
	v_mfma_f32_16x16x32_bf16 v[8:11], v[170:173], v[222:225], v[8:11]
	s_setprio 0
	s_setprio 1
	v_mfma_f32_16x16x32_bf16 v[52:55], v[174:177], v[190:193], 0
	v_mfma_f32_16x16x32_bf16 v[48:51], v[182:185], v[190:193], 0
	v_mfma_f32_16x16x32_bf16 v[36:39], v[174:177], v[198:201], 0
	v_mfma_f32_16x16x32_bf16 v[32:35], v[182:185], v[198:201], 0
	v_mfma_f32_16x16x32_bf16 v[20:23], v[174:177], v[206:209], 0
	v_mfma_f32_16x16x32_bf16 v[16:19], v[182:185], v[206:209], 0
	v_mfma_f32_16x16x32_bf16 v[4:7], v[174:177], v[218:221], 0
	v_mfma_f32_16x16x32_bf16 v[0:3], v[182:185], v[218:221], 0
	v_mfma_f32_16x16x32_bf16 v[52:55], v[178:181], v[194:197], v[52:55]
	v_mfma_f32_16x16x32_bf16 v[48:51], v[186:189], v[194:197], v[48:51]
	v_mfma_f32_16x16x32_bf16 v[36:39], v[178:181], v[202:205], v[36:39]
	v_mfma_f32_16x16x32_bf16 v[32:35], v[186:189], v[202:205], v[32:35]
	v_mfma_f32_16x16x32_bf16 v[20:23], v[178:181], v[214:217], v[20:23]
	v_mfma_f32_16x16x32_bf16 v[16:19], v[186:189], v[214:217], v[16:19]
	v_mfma_f32_16x16x32_bf16 v[4:7], v[178:181], v[222:225], v[4:7]
	v_mfma_f32_16x16x32_bf16 v[0:3], v[186:189], v[222:225], v[0:3]
	s_setprio 0
	s_barrier
	s_add_i32 s91, 0, 0x18000
	v_add_u32_e32 v136, s91, v162
	s_add_i32 s92, 0, 0x1c000
	ds_read_b128 v[146:149], v136
	ds_read_b128 v[150:153], v136 offset:1024
	ds_read_b128 v[154:157], v136 offset:2048
	ds_read_b128 v[170:173], v136 offset:3072
	v_add_u32_e32 v136, s92, v162
	ds_read_b128 v[174:177], v136
	ds_read_b128 v[178:181], v136 offset:1024
	ds_read_b128 v[182:185], v136 offset:2048
	ds_read_b128 v[186:189], v136 offset:3072
	s_add_u32 s78, s78, 0x80000
	s_addc_u32 s79, s79, 0
	s_mov_b32 m0, s28
	ds_read_b128 v[190:193], v168 offset:32768
	ds_read_b128 v[194:197], v168 offset:33792
	ds_read_b128 v[198:201], v168 offset:34816
	ds_read_b128 v[202:205], v168 offset:35840
	ds_read_b128 v[206:209], v168 offset:36864
	ds_read_b128 v[214:217], v168 offset:37888
	ds_read_b128 v[218:221], v168 offset:38912
	ds_read_b128 v[222:225], v168 offset:39936
	global_load_lds_dwordx4 v128, s[78:79]
	s_mov_b32 m0, s29
	s_nop 0
	global_load_lds_dwordx4 v132, s[78:79]
	s_waitcnt vmcnt(8)
	s_waitcnt lgkmcnt(0)
	s_setprio 1
	s_barrier
	v_mfma_f32_16x16x32_bf16 v[124:127], v[146:149], v[190:193], v[124:127]
	v_mfma_f32_16x16x32_bf16 v[120:123], v[154:157], v[190:193], v[120:123]
	v_mfma_f32_16x16x32_bf16 v[108:111], v[146:149], v[198:201], v[108:111]
	v_mfma_f32_16x16x32_bf16 v[104:107], v[154:157], v[198:201], v[104:107]
	v_mfma_f32_16x16x32_bf16 v[92:95], v[146:149], v[206:209], v[92:95]
	v_mfma_f32_16x16x32_bf16 v[88:91], v[154:157], v[206:209], v[88:91]
	v_mfma_f32_16x16x32_bf16 v[76:79], v[146:149], v[218:221], v[76:79]
	v_mfma_f32_16x16x32_bf16 v[72:75], v[154:157], v[218:221], v[72:75]
	v_mfma_f32_16x16x32_bf16 v[124:127], v[150:153], v[194:197], v[124:127]
	v_mfma_f32_16x16x32_bf16 v[120:123], v[170:173], v[194:197], v[120:123]
	v_mfma_f32_16x16x32_bf16 v[108:111], v[150:153], v[202:205], v[108:111]
	v_mfma_f32_16x16x32_bf16 v[104:107], v[170:173], v[202:205], v[104:107]
	v_mfma_f32_16x16x32_bf16 v[92:95], v[150:153], v[214:217], v[92:95]
	v_mfma_f32_16x16x32_bf16 v[88:91], v[170:173], v[214:217], v[88:91]
	v_mfma_f32_16x16x32_bf16 v[76:79], v[150:153], v[222:225], v[76:79]
	v_mfma_f32_16x16x32_bf16 v[72:75], v[170:173], v[222:225], v[72:75]
	s_setprio 0
	s_setprio 1
	v_mfma_f32_16x16x32_bf16 v[116:119], v[174:177], v[190:193], v[116:119]
	v_mfma_f32_16x16x32_bf16 v[112:115], v[182:185], v[190:193], v[112:115]
	v_mfma_f32_16x16x32_bf16 v[100:103], v[174:177], v[198:201], v[100:103]
	v_mfma_f32_16x16x32_bf16 v[96:99], v[182:185], v[198:201], v[96:99]
	v_mfma_f32_16x16x32_bf16 v[84:87], v[174:177], v[206:209], v[84:87]
	v_mfma_f32_16x16x32_bf16 v[80:83], v[182:185], v[206:209], v[80:83]
	v_mfma_f32_16x16x32_bf16 v[68:71], v[174:177], v[218:221], v[68:71]
	v_mfma_f32_16x16x32_bf16 v[64:67], v[182:185], v[218:221], v[64:67]
	v_mfma_f32_16x16x32_bf16 v[116:119], v[178:181], v[194:197], v[116:119]
	v_mfma_f32_16x16x32_bf16 v[112:115], v[186:189], v[194:197], v[112:115]
	v_mfma_f32_16x16x32_bf16 v[100:103], v[178:181], v[202:205], v[100:103]
	v_mfma_f32_16x16x32_bf16 v[96:99], v[186:189], v[202:205], v[96:99]
	v_mfma_f32_16x16x32_bf16 v[84:87], v[178:181], v[214:217], v[84:87]
	v_mfma_f32_16x16x32_bf16 v[80:83], v[186:189], v[214:217], v[80:83]
	v_mfma_f32_16x16x32_bf16 v[68:71], v[178:181], v[222:225], v[68:71]
	v_mfma_f32_16x16x32_bf16 v[64:67], v[186:189], v[222:225], v[64:67]
	s_setprio 0
	s_barrier
	s_add_i32 s78, s91, s30
	s_mov_b32 m0, s78
	ds_read_b128 v[190:193], v168 offset:49152
	ds_read_b128 v[194:197], v168 offset:50176
	ds_read_b128 v[198:201], v168 offset:51200
	ds_read_b128 v[202:205], v168 offset:52224
	ds_read_b128 v[206:209], v168 offset:53248
	ds_read_b128 v[214:217], v168 offset:54272
	ds_read_b128 v[218:221], v168 offset:55296
	ds_read_b128 v[222:225], v168 offset:56320
	global_load_lds_dwordx4 v130, s[98:99]
	s_add_i32 m0, s78, 0x2000
	s_add_u32 s76, s76, 0x80080
	s_addc_u32 s77, s77, 0
	s_add_i32 s78, s92, s30
	global_load_lds_dwordx4 v134, s[98:99]
	s_mov_b32 m0, s78
	s_nop 0
	global_load_lds_dwordx4 v130, s[76:77]
	s_add_i32 m0, s78, 0x2000
	s_nop 0
	global_load_lds_dwordx4 v134, s[76:77]
	s_mov_b32 m0, s73
	s_nop 0
	global_load_lds_dwordx4 v128, s[100:101]
	s_mov_b32 m0, s80
	s_nop 0
	global_load_lds_dwordx4 v132, s[100:101]
	s_waitcnt vmcnt(8)
	s_waitcnt lgkmcnt(0)
	s_setprio 1
	s_barrier
	v_mfma_f32_16x16x32_bf16 v[60:63], v[146:149], v[190:193], v[60:63]
	v_mfma_f32_16x16x32_bf16 v[56:59], v[154:157], v[190:193], v[56:59]
	v_mfma_f32_16x16x32_bf16 v[44:47], v[146:149], v[198:201], v[44:47]
	v_mfma_f32_16x16x32_bf16 v[40:43], v[154:157], v[198:201], v[40:43]
	v_mfma_f32_16x16x32_bf16 v[28:31], v[146:149], v[206:209], v[28:31]
	v_mfma_f32_16x16x32_bf16 v[24:27], v[154:157], v[206:209], v[24:27]
	v_mfma_f32_16x16x32_bf16 v[12:15], v[146:149], v[218:221], v[12:15]
	v_mfma_f32_16x16x32_bf16 v[8:11], v[154:157], v[218:221], v[8:11]
	v_mfma_f32_16x16x32_bf16 v[60:63], v[150:153], v[194:197], v[60:63]
	v_mfma_f32_16x16x32_bf16 v[56:59], v[170:173], v[194:197], v[56:59]
	v_mfma_f32_16x16x32_bf16 v[44:47], v[150:153], v[202:205], v[44:47]
	v_mfma_f32_16x16x32_bf16 v[40:43], v[170:173], v[202:205], v[40:43]
	v_mfma_f32_16x16x32_bf16 v[28:31], v[150:153], v[214:217], v[28:31]
	v_mfma_f32_16x16x32_bf16 v[24:27], v[170:173], v[214:217], v[24:27]
	v_mfma_f32_16x16x32_bf16 v[12:15], v[150:153], v[222:225], v[12:15]
	v_mfma_f32_16x16x32_bf16 v[8:11], v[170:173], v[222:225], v[8:11]
	s_setprio 0
	s_setprio 1
	v_mfma_f32_16x16x32_bf16 v[52:55], v[174:177], v[190:193], v[52:55]
	v_mfma_f32_16x16x32_bf16 v[48:51], v[182:185], v[190:193], v[48:51]
	v_mfma_f32_16x16x32_bf16 v[36:39], v[174:177], v[198:201], v[36:39]
	v_mfma_f32_16x16x32_bf16 v[32:35], v[182:185], v[198:201], v[32:35]
	v_mfma_f32_16x16x32_bf16 v[20:23], v[174:177], v[206:209], v[20:23]
	v_mfma_f32_16x16x32_bf16 v[16:19], v[182:185], v[206:209], v[16:19]
	v_mfma_f32_16x16x32_bf16 v[4:7], v[174:177], v[218:221], v[4:7]
	v_mfma_f32_16x16x32_bf16 v[0:3], v[182:185], v[218:221], v[0:3]
	v_mfma_f32_16x16x32_bf16 v[52:55], v[178:181], v[194:197], v[52:55]
	v_mfma_f32_16x16x32_bf16 v[48:51], v[186:189], v[194:197], v[48:51]
	v_mfma_f32_16x16x32_bf16 v[36:39], v[178:181], v[202:205], v[36:39]
	v_mfma_f32_16x16x32_bf16 v[32:35], v[186:189], v[202:205], v[32:35]
	v_mfma_f32_16x16x32_bf16 v[20:23], v[178:181], v[214:217], v[20:23]
	v_mfma_f32_16x16x32_bf16 v[16:19], v[186:189], v[214:217], v[16:19]
	v_mfma_f32_16x16x32_bf16 v[4:7], v[178:181], v[222:225], v[4:7]
	v_mfma_f32_16x16x32_bf16 v[0:3], v[186:189], v[222:225], v[0:3]
	s_setprio 0
	s_barrier
	s_add_i32 s90, s90, 2
	s_add_u32 s74, s74, 0x100
	s_addc_u32 s75, s75, 0
	s_add_u32 s65, s65, 0x100
	s_addc_u32 s71, s71, 0
	s_cmp_gt_u32 s90, 29
.LBB0_272:
	ds_read_b128 v[146:149], v166
	ds_read_b128 v[150:153], v166 offset:1024
	ds_read_b128 v[154:157], v166 offset:2048
	ds_read_b128 v[170:173], v166 offset:3072
	ds_read_b128 v[174:177], v167
	ds_read_b128 v[178:181], v167 offset:1024
	ds_read_b128 v[182:185], v167 offset:2048
	ds_read_b128 v[186:189], v167 offset:3072
	s_add_u32 s76, s74, 0xfff80080
	s_addc_u32 s77, s75, -1
	s_cmp_eq_u32 s90, 28
	s_cselect_b32 s79, s0, s77
	s_cselect_b32 s78, s1, s76
	s_cselect_b32 s77, s3, s71
	s_cselect_b32 s76, s63, s65
	s_add_i32 m0, s31, 0xc000
	ds_read_b128 v[190:193], v168
	ds_read_b128 v[194:197], v168 offset:1024
	ds_read_b128 v[198:201], v168 offset:2048
	ds_read_b128 v[202:205], v168 offset:3072
	ds_read_b128 v[206:209], v168 offset:4096
	ds_read_b128 v[214:217], v168 offset:5120
	ds_read_b128 v[218:221], v168 offset:6144
	ds_read_b128 v[222:225], v168 offset:7168
	global_load_lds_dwordx4 v138, s[74:75]
	s_add_i32 m0, s31, 0xe000
	s_nop 0
	global_load_lds_dwordx4 v140, s[74:75]
	s_waitcnt vmcnt(8)
	s_waitcnt lgkmcnt(0)
	s_setprio 1
	s_barrier
	v_mfma_f32_16x16x32_bf16 v[124:127], v[146:149], v[190:193], v[124:127]
	v_mfma_f32_16x16x32_bf16 v[120:123], v[154:157], v[190:193], v[120:123]
	v_mfma_f32_16x16x32_bf16 v[108:111], v[146:149], v[198:201], v[108:111]
	v_mfma_f32_16x16x32_bf16 v[104:107], v[154:157], v[198:201], v[104:107]
	v_mfma_f32_16x16x32_bf16 v[92:95], v[146:149], v[206:209], v[92:95]
	v_mfma_f32_16x16x32_bf16 v[88:91], v[154:157], v[206:209], v[88:91]
	v_mfma_f32_16x16x32_bf16 v[76:79], v[146:149], v[218:221], v[76:79]
	v_mfma_f32_16x16x32_bf16 v[72:75], v[154:157], v[218:221], v[72:75]
	v_mfma_f32_16x16x32_bf16 v[124:127], v[150:153], v[194:197], v[124:127]
	v_mfma_f32_16x16x32_bf16 v[120:123], v[170:173], v[194:197], v[120:123]
	v_mfma_f32_16x16x32_bf16 v[108:111], v[150:153], v[202:205], v[108:111]
	v_mfma_f32_16x16x32_bf16 v[104:107], v[170:173], v[202:205], v[104:107]
	v_mfma_f32_16x16x32_bf16 v[92:95], v[150:153], v[214:217], v[92:95]
	v_mfma_f32_16x16x32_bf16 v[88:91], v[170:173], v[214:217], v[88:91]
	v_mfma_f32_16x16x32_bf16 v[76:79], v[150:153], v[222:225], v[76:79]
	v_mfma_f32_16x16x32_bf16 v[72:75], v[170:173], v[222:225], v[72:75]
	s_setprio 0
	s_setprio 1
	v_mfma_f32_16x16x32_bf16 v[116:119], v[174:177], v[190:193], v[116:119]
	v_mfma_f32_16x16x32_bf16 v[112:115], v[182:185], v[190:193], v[112:115]
	v_mfma_f32_16x16x32_bf16 v[100:103], v[174:177], v[198:201], v[100:103]
	v_mfma_f32_16x16x32_bf16 v[96:99], v[182:185], v[198:201], v[96:99]
	v_mfma_f32_16x16x32_bf16 v[84:87], v[174:177], v[206:209], v[84:87]
	v_mfma_f32_16x16x32_bf16 v[80:83], v[182:185], v[206:209], v[80:83]
	v_mfma_f32_16x16x32_bf16 v[68:71], v[174:177], v[218:221], v[68:71]
	v_mfma_f32_16x16x32_bf16 v[64:67], v[182:185], v[218:221], v[64:67]
	v_mfma_f32_16x16x32_bf16 v[116:119], v[178:181], v[194:197], v[116:119]
	v_mfma_f32_16x16x32_bf16 v[112:115], v[186:189], v[194:197], v[112:115]
	v_mfma_f32_16x16x32_bf16 v[100:103], v[178:181], v[202:205], v[100:103]
	v_mfma_f32_16x16x32_bf16 v[96:99], v[186:189], v[202:205], v[96:99]
	v_mfma_f32_16x16x32_bf16 v[84:87], v[178:181], v[214:217], v[84:87]
	v_mfma_f32_16x16x32_bf16 v[80:83], v[186:189], v[214:217], v[80:83]
	v_mfma_f32_16x16x32_bf16 v[68:71], v[178:181], v[222:225], v[68:71]
	v_mfma_f32_16x16x32_bf16 v[64:67], v[186:189], v[222:225], v[64:67]
	s_setprio 0
	s_barrier
	s_add_i32 s91, s81, s30
	s_add_u32 s98, s76, s34
	s_addc_u32 s99, s77, s35
	s_mov_b32 m0, s91
	ds_read_b128 v[190:193], v168 offset:16384
	ds_read_b128 v[194:197], v168 offset:17408
	ds_read_b128 v[198:201], v168 offset:18432
	ds_read_b128 v[202:205], v168 offset:19456
	ds_read_b128 v[206:209], v168 offset:20480
	ds_read_b128 v[214:217], v168 offset:21504
	ds_read_b128 v[218:221], v168 offset:22528
	ds_read_b128 v[222:225], v168 offset:23552
	global_load_lds_dwordx4 v130, s[76:77]
	s_add_i32 m0, s91, 0x2000
	s_add_u32 s92, s76, 0x80000
	s_addc_u32 s93, s77, 0
	s_add_i32 s91, s83, s30
	global_load_lds_dwordx4 v134, s[76:77]
	s_mov_b32 m0, s91
	s_add_u32 s100, s78, s34
	s_addc_u32 s101, s79, s35
	global_load_lds_dwordx4 v130, s[92:93]
	s_add_i32 m0, s91, 0x2000
	s_nop 0
	global_load_lds_dwordx4 v134, s[92:93]
	s_mov_b32 m0, s31
	s_nop 0
	global_load_lds_dwordx4 v128, s[78:79]
	s_mov_b32 m0, s51
	s_nop 0
	global_load_lds_dwordx4 v132, s[78:79]
	s_waitcnt vmcnt(8)
	s_waitcnt lgkmcnt(0)
	s_setprio 1
	s_barrier
	v_mfma_f32_16x16x32_bf16 v[60:63], v[146:149], v[190:193], v[60:63]
	v_mfma_f32_16x16x32_bf16 v[56:59], v[154:157], v[190:193], v[56:59]
	v_mfma_f32_16x16x32_bf16 v[44:47], v[146:149], v[198:201], v[44:47]
	v_mfma_f32_16x16x32_bf16 v[40:43], v[154:157], v[198:201], v[40:43]
	v_mfma_f32_16x16x32_bf16 v[28:31], v[146:149], v[206:209], v[28:31]
	v_mfma_f32_16x16x32_bf16 v[24:27], v[154:157], v[206:209], v[24:27]
	v_mfma_f32_16x16x32_bf16 v[12:15], v[146:149], v[218:221], v[12:15]
	v_mfma_f32_16x16x32_bf16 v[8:11], v[154:157], v[218:221], v[8:11]
	v_mfma_f32_16x16x32_bf16 v[60:63], v[150:153], v[194:197], v[60:63]
	v_mfma_f32_16x16x32_bf16 v[56:59], v[170:173], v[194:197], v[56:59]
	v_mfma_f32_16x16x32_bf16 v[44:47], v[150:153], v[202:205], v[44:47]
	v_mfma_f32_16x16x32_bf16 v[40:43], v[170:173], v[202:205], v[40:43]
	v_mfma_f32_16x16x32_bf16 v[28:31], v[150:153], v[214:217], v[28:31]
	v_mfma_f32_16x16x32_bf16 v[24:27], v[170:173], v[214:217], v[24:27]
	v_mfma_f32_16x16x32_bf16 v[12:15], v[150:153], v[222:225], v[12:15]
	v_mfma_f32_16x16x32_bf16 v[8:11], v[170:173], v[222:225], v[8:11]
	s_setprio 0
	s_setprio 1
	v_mfma_f32_16x16x32_bf16 v[52:55], v[174:177], v[190:193], v[52:55]
	v_mfma_f32_16x16x32_bf16 v[48:51], v[182:185], v[190:193], v[48:51]
	v_mfma_f32_16x16x32_bf16 v[36:39], v[174:177], v[198:201], v[36:39]
	v_mfma_f32_16x16x32_bf16 v[32:35], v[182:185], v[198:201], v[32:35]
	v_mfma_f32_16x16x32_bf16 v[20:23], v[174:177], v[206:209], v[20:23]
	v_mfma_f32_16x16x32_bf16 v[16:19], v[182:185], v[206:209], v[16:19]
	v_mfma_f32_16x16x32_bf16 v[4:7], v[174:177], v[218:221], v[4:7]
	v_mfma_f32_16x16x32_bf16 v[0:3], v[182:185], v[218:221], v[0:3]
	v_mfma_f32_16x16x32_bf16 v[52:55], v[178:181], v[194:197], v[52:55]
	v_mfma_f32_16x16x32_bf16 v[48:51], v[186:189], v[194:197], v[48:51]
	v_mfma_f32_16x16x32_bf16 v[36:39], v[178:181], v[202:205], v[36:39]
	v_mfma_f32_16x16x32_bf16 v[32:35], v[186:189], v[202:205], v[32:35]
	v_mfma_f32_16x16x32_bf16 v[20:23], v[178:181], v[214:217], v[20:23]
	v_mfma_f32_16x16x32_bf16 v[16:19], v[186:189], v[214:217], v[16:19]
	v_mfma_f32_16x16x32_bf16 v[4:7], v[178:181], v[222:225], v[4:7]
	v_mfma_f32_16x16x32_bf16 v[0:3], v[186:189], v[222:225], v[0:3]
	s_setprio 0
	s_barrier
	s_add_i32 s91, 0, 0x18000
	v_add_u32_e32 v136, s91, v162
	s_add_i32 s92, 0, 0x1c000
	ds_read_b128 v[146:149], v136
	ds_read_b128 v[150:153], v136 offset:1024
	ds_read_b128 v[154:157], v136 offset:2048
	ds_read_b128 v[170:173], v136 offset:3072
	v_add_u32_e32 v136, s92, v162
	ds_read_b128 v[174:177], v136
	ds_read_b128 v[178:181], v136 offset:1024
	ds_read_b128 v[182:185], v136 offset:2048
	ds_read_b128 v[186:189], v136 offset:3072
	s_add_u32 s78, s78, 0x80000
	s_addc_u32 s79, s79, 0
	s_mov_b32 m0, s28
	ds_read_b128 v[190:193], v168 offset:32768
	ds_read_b128 v[194:197], v168 offset:33792
	ds_read_b128 v[198:201], v168 offset:34816
	ds_read_b128 v[202:205], v168 offset:35840
	ds_read_b128 v[206:209], v168 offset:36864
	ds_read_b128 v[214:217], v168 offset:37888
	ds_read_b128 v[218:221], v168 offset:38912
	ds_read_b128 v[222:225], v168 offset:39936
	global_load_lds_dwordx4 v128, s[78:79]
	s_mov_b32 m0, s29
	s_nop 0
	global_load_lds_dwordx4 v132, s[78:79]
	s_waitcnt vmcnt(8)
	s_waitcnt lgkmcnt(0)
	s_setprio 1
	s_barrier
	v_mfma_f32_16x16x32_bf16 v[124:127], v[146:149], v[190:193], v[124:127]
	v_mfma_f32_16x16x32_bf16 v[120:123], v[154:157], v[190:193], v[120:123]
	v_mfma_f32_16x16x32_bf16 v[108:111], v[146:149], v[198:201], v[108:111]
	v_mfma_f32_16x16x32_bf16 v[104:107], v[154:157], v[198:201], v[104:107]
	v_mfma_f32_16x16x32_bf16 v[92:95], v[146:149], v[206:209], v[92:95]
	v_mfma_f32_16x16x32_bf16 v[88:91], v[154:157], v[206:209], v[88:91]
	v_mfma_f32_16x16x32_bf16 v[76:79], v[146:149], v[218:221], v[76:79]
	v_mfma_f32_16x16x32_bf16 v[72:75], v[154:157], v[218:221], v[72:75]
	v_mfma_f32_16x16x32_bf16 v[124:127], v[150:153], v[194:197], v[124:127]
	v_mfma_f32_16x16x32_bf16 v[120:123], v[170:173], v[194:197], v[120:123]
	v_mfma_f32_16x16x32_bf16 v[108:111], v[150:153], v[202:205], v[108:111]
	v_mfma_f32_16x16x32_bf16 v[104:107], v[170:173], v[202:205], v[104:107]
	v_mfma_f32_16x16x32_bf16 v[92:95], v[150:153], v[214:217], v[92:95]
	v_mfma_f32_16x16x32_bf16 v[88:91], v[170:173], v[214:217], v[88:91]
	v_mfma_f32_16x16x32_bf16 v[76:79], v[150:153], v[222:225], v[76:79]
	v_mfma_f32_16x16x32_bf16 v[72:75], v[170:173], v[222:225], v[72:75]
	s_setprio 0
	s_setprio 1
	v_mfma_f32_16x16x32_bf16 v[116:119], v[174:177], v[190:193], v[116:119]
	v_mfma_f32_16x16x32_bf16 v[112:115], v[182:185], v[190:193], v[112:115]
	v_mfma_f32_16x16x32_bf16 v[100:103], v[174:177], v[198:201], v[100:103]
	v_mfma_f32_16x16x32_bf16 v[96:99], v[182:185], v[198:201], v[96:99]
	v_mfma_f32_16x16x32_bf16 v[84:87], v[174:177], v[206:209], v[84:87]
	v_mfma_f32_16x16x32_bf16 v[80:83], v[182:185], v[206:209], v[80:83]
	v_mfma_f32_16x16x32_bf16 v[68:71], v[174:177], v[218:221], v[68:71]
	v_mfma_f32_16x16x32_bf16 v[64:67], v[182:185], v[218:221], v[64:67]
	v_mfma_f32_16x16x32_bf16 v[116:119], v[178:181], v[194:197], v[116:119]
	v_mfma_f32_16x16x32_bf16 v[112:115], v[186:189], v[194:197], v[112:115]
	v_mfma_f32_16x16x32_bf16 v[100:103], v[178:181], v[202:205], v[100:103]
	v_mfma_f32_16x16x32_bf16 v[96:99], v[186:189], v[202:205], v[96:99]
	v_mfma_f32_16x16x32_bf16 v[84:87], v[178:181], v[214:217], v[84:87]
	v_mfma_f32_16x16x32_bf16 v[80:83], v[186:189], v[214:217], v[80:83]
	v_mfma_f32_16x16x32_bf16 v[68:71], v[178:181], v[222:225], v[68:71]
	v_mfma_f32_16x16x32_bf16 v[64:67], v[186:189], v[222:225], v[64:67]
	s_setprio 0
	s_barrier
	s_add_i32 s78, s91, s30
	s_mov_b32 m0, s78
	ds_read_b128 v[190:193], v168 offset:49152
	ds_read_b128 v[194:197], v168 offset:50176
	ds_read_b128 v[198:201], v168 offset:51200
	ds_read_b128 v[202:205], v168 offset:52224
	ds_read_b128 v[206:209], v168 offset:53248
	ds_read_b128 v[214:217], v168 offset:54272
	ds_read_b128 v[218:221], v168 offset:55296
	ds_read_b128 v[222:225], v168 offset:56320
	global_load_lds_dwordx4 v130, s[98:99]
	s_add_i32 m0, s78, 0x2000
	s_add_u32 s76, s76, 0x80080
	s_addc_u32 s77, s77, 0
	s_add_i32 s78, s92, s30
	global_load_lds_dwordx4 v134, s[98:99]
	s_mov_b32 m0, s78
	s_nop 0
	global_load_lds_dwordx4 v130, s[76:77]
	s_add_i32 m0, s78, 0x2000
	s_nop 0
	global_load_lds_dwordx4 v134, s[76:77]
	s_mov_b32 m0, s73
	s_nop 0
	global_load_lds_dwordx4 v128, s[100:101]
	s_mov_b32 m0, s80
	s_nop 0
	global_load_lds_dwordx4 v132, s[100:101]
	s_waitcnt vmcnt(8)
	s_waitcnt lgkmcnt(0)
	s_setprio 1
	s_barrier
	v_mfma_f32_16x16x32_bf16 v[60:63], v[146:149], v[190:193], v[60:63]
	v_mfma_f32_16x16x32_bf16 v[56:59], v[154:157], v[190:193], v[56:59]
	v_mfma_f32_16x16x32_bf16 v[44:47], v[146:149], v[198:201], v[44:47]
	v_mfma_f32_16x16x32_bf16 v[40:43], v[154:157], v[198:201], v[40:43]
	v_mfma_f32_16x16x32_bf16 v[28:31], v[146:149], v[206:209], v[28:31]
	v_mfma_f32_16x16x32_bf16 v[24:27], v[154:157], v[206:209], v[24:27]
	v_mfma_f32_16x16x32_bf16 v[12:15], v[146:149], v[218:221], v[12:15]
	v_mfma_f32_16x16x32_bf16 v[8:11], v[154:157], v[218:221], v[8:11]
	v_mfma_f32_16x16x32_bf16 v[60:63], v[150:153], v[194:197], v[60:63]
	v_mfma_f32_16x16x32_bf16 v[56:59], v[170:173], v[194:197], v[56:59]
	v_mfma_f32_16x16x32_bf16 v[44:47], v[150:153], v[202:205], v[44:47]
	v_mfma_f32_16x16x32_bf16 v[40:43], v[170:173], v[202:205], v[40:43]
	v_mfma_f32_16x16x32_bf16 v[28:31], v[150:153], v[214:217], v[28:31]
	v_mfma_f32_16x16x32_bf16 v[24:27], v[170:173], v[214:217], v[24:27]
	v_mfma_f32_16x16x32_bf16 v[12:15], v[150:153], v[222:225], v[12:15]
	v_mfma_f32_16x16x32_bf16 v[8:11], v[170:173], v[222:225], v[8:11]
	s_setprio 0
	s_setprio 1
	v_mfma_f32_16x16x32_bf16 v[52:55], v[174:177], v[190:193], v[52:55]
	v_mfma_f32_16x16x32_bf16 v[48:51], v[182:185], v[190:193], v[48:51]
	v_mfma_f32_16x16x32_bf16 v[36:39], v[174:177], v[198:201], v[36:39]
	v_mfma_f32_16x16x32_bf16 v[32:35], v[182:185], v[198:201], v[32:35]
	v_mfma_f32_16x16x32_bf16 v[20:23], v[174:177], v[206:209], v[20:23]
	v_mfma_f32_16x16x32_bf16 v[16:19], v[182:185], v[206:209], v[16:19]
	v_mfma_f32_16x16x32_bf16 v[4:7], v[174:177], v[218:221], v[4:7]
	v_mfma_f32_16x16x32_bf16 v[0:3], v[182:185], v[218:221], v[0:3]
	v_mfma_f32_16x16x32_bf16 v[52:55], v[178:181], v[194:197], v[52:55]
	v_mfma_f32_16x16x32_bf16 v[48:51], v[186:189], v[194:197], v[48:51]
	v_mfma_f32_16x16x32_bf16 v[36:39], v[178:181], v[202:205], v[36:39]
	v_mfma_f32_16x16x32_bf16 v[32:35], v[186:189], v[202:205], v[32:35]
	v_mfma_f32_16x16x32_bf16 v[20:23], v[178:181], v[214:217], v[20:23]
	v_mfma_f32_16x16x32_bf16 v[16:19], v[186:189], v[214:217], v[16:19]
	v_mfma_f32_16x16x32_bf16 v[4:7], v[178:181], v[222:225], v[4:7]
	v_mfma_f32_16x16x32_bf16 v[0:3], v[186:189], v[222:225], v[0:3]
	s_setprio 0
	s_barrier
	s_add_i32 s90, s90, 2
	s_add_u32 s74, s74, 0x100
	s_addc_u32 s75, s75, 0
	s_add_u32 s65, s65, 0x100
	s_addc_u32 s71, s71, 0
	s_cmp_gt_u32 s90, 29
	s_cbranch_scc0 .LBB0_272
	s_and_b64 vcc, exec, s[36:37]
	s_cbranch_vccz .LBB0_275
	s_barrier

.LBB0_542:
	s_ashr_i32 s35, s34, 31
	s_lshl_b64 s[0:1], s[34:35], 20
	s_add_u32 s36, s29, s0
	s_addc_u32 s37, s30, s1
	s_and_b64 s[0:1], s[6:7], exec
	s_cselect_b32 s0, s37, s43
	s_cselect_b32 s1, s36, s42
	s_ashr_i32 s25, s24, 31
	s_lshl_b64 s[38:39], s[24:25], 20
	s_add_u32 s38, s27, s38
	s_addc_u32 s39, s28, s39
	s_and_b64 s[46:47], s[6:7], exec
	s_cselect_b32 s3, s39, s45
	s_cselect_b32 s9, s38, s44
	s_add_u32 s42, s42, 0x80080
	s_addc_u32 s43, s43, 0
	s_add_u32 s25, s44, 0x100
	s_addc_u32 s35, s45, 0
	s_mov_b32 s58, -2
	s_waitcnt lgkmcnt(0)
	s_waitcnt vmcnt(0)
	ds_read_b128 v[128:131], v216
	ds_read_b128 v[132:135], v216 offset:1024
	ds_read_b128 v[136:139], v216 offset:2048
	ds_read_b128 v[140:143], v216 offset:3072
	ds_read_b128 v[144:147], v217
	ds_read_b128 v[148:151], v217 offset:1024
	ds_read_b128 v[152:155], v217 offset:2048
	ds_read_b128 v[156:159], v217 offset:3072
	s_add_u32 s44, s42, 0xfff80080
	s_addc_u32 s45, s43, -1
	s_cmp_eq_u32 s58, 28
	s_cselect_b32 s47, s0, s45
	s_cselect_b32 s46, s1, s44
	s_cselect_b32 s45, s3, s35
	s_cselect_b32 s44, s9, s25
	s_add_i32 m0, s41, 0xc000
	ds_read_b128 v[160:163], v218
	ds_read_b128 v[164:167], v218 offset:1024
	ds_read_b128 v[168:171], v218 offset:2048
	ds_read_b128 v[172:175], v218 offset:3072
	ds_read_b128 v[192:195], v218 offset:4096
	ds_read_b128 v[196:199], v218 offset:5120
	ds_read_b128 v[200:203], v218 offset:6144
	ds_read_b128 v[204:207], v218 offset:7168
	global_load_lds_dwordx4 v184, s[42:43]
	s_add_i32 m0, s41, 0xe000
	s_nop 0
	global_load_lds_dwordx4 v186, s[42:43]
	s_waitcnt vmcnt(8)
	s_waitcnt lgkmcnt(0)
	s_setprio 1
	s_barrier
	v_mfma_f32_16x16x32_bf16 v[124:127], v[128:131], v[160:163], 0
	v_mfma_f32_16x16x32_bf16 v[120:123], v[136:139], v[160:163], 0
	v_mfma_f32_16x16x32_bf16 v[108:111], v[128:131], v[168:171], 0
	v_mfma_f32_16x16x32_bf16 v[104:107], v[136:139], v[168:171], 0
	v_mfma_f32_16x16x32_bf16 v[92:95], v[128:131], v[192:195], 0
	v_mfma_f32_16x16x32_bf16 v[88:91], v[136:139], v[192:195], 0
	v_mfma_f32_16x16x32_bf16 v[76:79], v[128:131], v[200:203], 0
	v_mfma_f32_16x16x32_bf16 v[72:75], v[136:139], v[200:203], 0
	v_mfma_f32_16x16x32_bf16 v[124:127], v[132:135], v[164:167], v[124:127]
	v_mfma_f32_16x16x32_bf16 v[120:123], v[140:143], v[164:167], v[120:123]
	v_mfma_f32_16x16x32_bf16 v[108:111], v[132:135], v[172:175], v[108:111]
	v_mfma_f32_16x16x32_bf16 v[104:107], v[140:143], v[172:175], v[104:107]
	v_mfma_f32_16x16x32_bf16 v[92:95], v[132:135], v[196:199], v[92:95]
	v_mfma_f32_16x16x32_bf16 v[88:91], v[140:143], v[196:199], v[88:91]
	v_mfma_f32_16x16x32_bf16 v[76:79], v[132:135], v[204:207], v[76:79]
	v_mfma_f32_16x16x32_bf16 v[72:75], v[140:143], v[204:207], v[72:75]
	s_setprio 0
	s_setprio 1
	v_mfma_f32_16x16x32_bf16 v[116:119], v[144:147], v[160:163], 0
	v_mfma_f32_16x16x32_bf16 v[112:115], v[152:155], v[160:163], 0
	v_mfma_f32_16x16x32_bf16 v[100:103], v[144:147], v[168:171], 0
	v_mfma_f32_16x16x32_bf16 v[96:99], v[152:155], v[168:171], 0
	v_mfma_f32_16x16x32_bf16 v[84:87], v[144:147], v[192:195], 0
	v_mfma_f32_16x16x32_bf16 v[80:83], v[152:155], v[192:195], 0
	v_mfma_f32_16x16x32_bf16 v[68:71], v[144:147], v[200:203], 0
	v_mfma_f32_16x16x32_bf16 v[64:67], v[152:155], v[200:203], 0
	v_mfma_f32_16x16x32_bf16 v[116:119], v[148:151], v[164:167], v[116:119]
	v_mfma_f32_16x16x32_bf16 v[112:115], v[156:159], v[164:167], v[112:115]
	v_mfma_f32_16x16x32_bf16 v[100:103], v[148:151], v[172:175], v[100:103]
	v_mfma_f32_16x16x32_bf16 v[96:99], v[156:159], v[172:175], v[96:99]
	v_mfma_f32_16x16x32_bf16 v[84:87], v[148:151], v[196:199], v[84:87]
	v_mfma_f32_16x16x32_bf16 v[80:83], v[156:159], v[196:199], v[80:83]
	v_mfma_f32_16x16x32_bf16 v[68:71], v[148:151], v[204:207], v[68:71]
	v_mfma_f32_16x16x32_bf16 v[64:67], v[156:159], v[204:207], v[64:67]
	s_setprio 0
	s_barrier
	s_add_i32 s59, s55, s31
	s_add_u32 s98, s44, s20
	s_addc_u32 s99, s45, s21
	s_mov_b32 m0, s59
	ds_read_b128 v[160:163], v218 offset:16384
	ds_read_b128 v[164:167], v218 offset:17408
	ds_read_b128 v[168:171], v218 offset:18432
	ds_read_b128 v[172:175], v218 offset:19456
	ds_read_b128 v[192:195], v218 offset:20480
	ds_read_b128 v[196:199], v218 offset:21504
	ds_read_b128 v[200:203], v218 offset:22528
	ds_read_b128 v[204:207], v218 offset:23552
	global_load_lds_dwordx4 v178, s[44:45]
	s_add_i32 m0, s59, 0x2000
	s_add_u32 s60, s44, 0x80000
	s_addc_u32 s61, s45, 0
	s_add_i32 s59, s56, s31
	global_load_lds_dwordx4 v182, s[44:45]
	s_mov_b32 m0, s59
	s_add_u32 s100, s46, s20
	s_addc_u32 s101, s47, s21
	global_load_lds_dwordx4 v178, s[60:61]
	s_add_i32 m0, s59, 0x2000
	s_nop 0
	global_load_lds_dwordx4 v182, s[60:61]
	s_mov_b32 m0, s41
	s_nop 0
	global_load_lds_dwordx4 v176, s[46:47]
	s_mov_b32 m0, s48
	s_nop 0
	global_load_lds_dwordx4 v180, s[46:47]
	s_waitcnt vmcnt(8)
	s_waitcnt lgkmcnt(0)
	s_setprio 1
	s_barrier
	v_mfma_f32_16x16x32_bf16 v[60:63], v[128:131], v[160:163], 0
	v_mfma_f32_16x16x32_bf16 v[56:59], v[136:139], v[160:163], 0
	v_mfma_f32_16x16x32_bf16 v[44:47], v[128:131], v[168:171], 0
	v_mfma_f32_16x16x32_bf16 v[40:43], v[136:139], v[168:171], 0
	v_mfma_f32_16x16x32_bf16 v[28:31], v[128:131], v[192:195], 0
	v_mfma_f32_16x16x32_bf16 v[24:27], v[136:139], v[192:195], 0
	v_mfma_f32_16x16x32_bf16 v[12:15], v[128:131], v[200:203], 0
	v_mfma_f32_16x16x32_bf16 v[8:11], v[136:139], v[200:203], 0
	v_mfma_f32_16x16x32_bf16 v[60:63], v[132:135], v[164:167], v[60:63]
	v_mfma_f32_16x16x32_bf16 v[56:59], v[140:143], v[164:167], v[56:59]
	v_mfma_f32_16x16x32_bf16 v[44:47], v[132:135], v[172:175], v[44:47]
	v_mfma_f32_16x16x32_bf16 v[40:43], v[140:143], v[172:175], v[40:43]
	v_mfma_f32_16x16x32_bf16 v[28:31], v[132:135], v[196:199], v[28:31]
	v_mfma_f32_16x16x32_bf16 v[24:27], v[140:143], v[196:199], v[24:27]
	v_mfma_f32_16x16x32_bf16 v[12:15], v[132:135], v[204:207], v[12:15]
	v_mfma_f32_16x16x32_bf16 v[8:11], v[140:143], v[204:207], v[8:11]
	s_setprio 0
	s_setprio 1
	v_mfma_f32_16x16x32_bf16 v[52:55], v[144:147], v[160:163], 0
	v_mfma_f32_16x16x32_bf16 v[48:51], v[152:155], v[160:163], 0
	v_mfma_f32_16x16x32_bf16 v[36:39], v[144:147], v[168:171], 0
	v_mfma_f32_16x16x32_bf16 v[32:35], v[152:155], v[168:171], 0
	v_mfma_f32_16x16x32_bf16 v[20:23], v[144:147], v[192:195], 0
	v_mfma_f32_16x16x32_bf16 v[16:19], v[152:155], v[192:195], 0
	v_mfma_f32_16x16x32_bf16 v[4:7], v[144:147], v[200:203], 0
	v_mfma_f32_16x16x32_bf16 v[0:3], v[152:155], v[200:203], 0
	v_mfma_f32_16x16x32_bf16 v[52:55], v[148:151], v[164:167], v[52:55]
	v_mfma_f32_16x16x32_bf16 v[48:51], v[156:159], v[164:167], v[48:51]
	v_mfma_f32_16x16x32_bf16 v[36:39], v[148:151], v[172:175], v[36:39]
	v_mfma_f32_16x16x32_bf16 v[32:35], v[156:159], v[172:175], v[32:35]
	v_mfma_f32_16x16x32_bf16 v[20:23], v[148:151], v[196:199], v[20:23]
	v_mfma_f32_16x16x32_bf16 v[16:19], v[156:159], v[196:199], v[16:19]
	v_mfma_f32_16x16x32_bf16 v[4:7], v[148:151], v[204:207], v[4:7]
	v_mfma_f32_16x16x32_bf16 v[0:3], v[156:159], v[204:207], v[0:3]
	s_setprio 0
	s_barrier
	s_add_i32 s59, 0, 0x18000
	s_add_i32 s60, 0, 0x1c000
	v_add_u32_e32 v140, s59, v214
	v_add_u32_e32 v156, s60, v214
	ds_read_b128 v[128:131], v140
	ds_read_b128 v[132:135], v140 offset:1024
	ds_read_b128 v[136:139], v140 offset:2048
	ds_read_b128 v[140:143], v140 offset:3072
	ds_read_b128 v[144:147], v156
	ds_read_b128 v[148:151], v156 offset:1024
	ds_read_b128 v[152:155], v156 offset:2048
	ds_read_b128 v[156:159], v156 offset:3072
	s_add_u32 s46, s46, 0x80000
	s_addc_u32 s47, s47, 0
	s_mov_b32 m0, s49
	ds_read_b128 v[160:163], v218 offset:32768
	ds_read_b128 v[164:167], v218 offset:33792
	ds_read_b128 v[168:171], v218 offset:34816
	ds_read_b128 v[172:175], v218 offset:35840
	ds_read_b128 v[192:195], v218 offset:36864
	ds_read_b128 v[196:199], v218 offset:37888
	ds_read_b128 v[200:203], v218 offset:38912
	ds_read_b128 v[204:207], v218 offset:39936
	global_load_lds_dwordx4 v176, s[46:47]
	s_mov_b32 m0, s50
	s_nop 0
	global_load_lds_dwordx4 v180, s[46:47]
	s_waitcnt vmcnt(8)
	s_waitcnt lgkmcnt(0)
	s_setprio 1
	s_barrier
	v_mfma_f32_16x16x32_bf16 v[124:127], v[128:131], v[160:163], v[124:127]
	v_mfma_f32_16x16x32_bf16 v[120:123], v[136:139], v[160:163], v[120:123]
	v_mfma_f32_16x16x32_bf16 v[108:111], v[128:131], v[168:171], v[108:111]
	v_mfma_f32_16x16x32_bf16 v[104:107], v[136:139], v[168:171], v[104:107]
	v_mfma_f32_16x16x32_bf16 v[92:95], v[128:131], v[192:195], v[92:95]
	v_mfma_f32_16x16x32_bf16 v[88:91], v[136:139], v[192:195], v[88:91]
	v_mfma_f32_16x16x32_bf16 v[76:79], v[128:131], v[200:203], v[76:79]
	v_mfma_f32_16x16x32_bf16 v[72:75], v[136:139], v[200:203], v[72:75]
	v_mfma_f32_16x16x32_bf16 v[124:127], v[132:135], v[164:167], v[124:127]
	v_mfma_f32_16x16x32_bf16 v[120:123], v[140:143], v[164:167], v[120:123]
	v_mfma_f32_16x16x32_bf16 v[108:111], v[132:135], v[172:175], v[108:111]
	v_mfma_f32_16x16x32_bf16 v[104:107], v[140:143], v[172:175], v[104:107]
	v_mfma_f32_16x16x32_bf16 v[92:95], v[132:135], v[196:199], v[92:95]
	v_mfma_f32_16x16x32_bf16 v[88:91], v[140:143], v[196:199], v[88:91]
	v_mfma_f32_16x16x32_bf16 v[76:79], v[132:135], v[204:207], v[76:79]
	v_mfma_f32_16x16x32_bf16 v[72:75], v[140:143], v[204:207], v[72:75]
	s_setprio 0
	s_setprio 1
	v_mfma_f32_16x16x32_bf16 v[116:119], v[144:147], v[160:163], v[116:119]
	v_mfma_f32_16x16x32_bf16 v[112:115], v[152:155], v[160:163], v[112:115]
	v_mfma_f32_16x16x32_bf16 v[100:103], v[144:147], v[168:171], v[100:103]
	v_mfma_f32_16x16x32_bf16 v[96:99], v[152:155], v[168:171], v[96:99]
	v_mfma_f32_16x16x32_bf16 v[84:87], v[144:147], v[192:195], v[84:87]
	v_mfma_f32_16x16x32_bf16 v[80:83], v[152:155], v[192:195], v[80:83]
	v_mfma_f32_16x16x32_bf16 v[68:71], v[144:147], v[200:203], v[68:71]
	v_mfma_f32_16x16x32_bf16 v[64:67], v[152:155], v[200:203], v[64:67]
	v_mfma_f32_16x16x32_bf16 v[116:119], v[148:151], v[164:167], v[116:119]
	v_mfma_f32_16x16x32_bf16 v[112:115], v[156:159], v[164:167], v[112:115]
	v_mfma_f32_16x16x32_bf16 v[100:103], v[148:151], v[172:175], v[100:103]
	v_mfma_f32_16x16x32_bf16 v[96:99], v[156:159], v[172:175], v[96:99]
	v_mfma_f32_16x16x32_bf16 v[84:87], v[148:151], v[196:199], v[84:87]
	v_mfma_f32_16x16x32_bf16 v[80:83], v[156:159], v[196:199], v[80:83]
	v_mfma_f32_16x16x32_bf16 v[68:71], v[148:151], v[204:207], v[68:71]
	v_mfma_f32_16x16x32_bf16 v[64:67], v[156:159], v[204:207], v[64:67]
	s_setprio 0
	s_barrier
	s_add_i32 s46, s59, s31
	s_mov_b32 m0, s46
	ds_read_b128 v[160:163], v218 offset:49152
	ds_read_b128 v[164:167], v218 offset:50176
	ds_read_b128 v[168:171], v218 offset:51200
	ds_read_b128 v[172:175], v218 offset:52224
	ds_read_b128 v[192:195], v218 offset:53248
	ds_read_b128 v[196:199], v218 offset:54272
	ds_read_b128 v[200:203], v218 offset:55296
	ds_read_b128 v[204:207], v218 offset:56320
	global_load_lds_dwordx4 v178, s[98:99]
	s_add_i32 m0, s46, 0x2000
	s_add_u32 s44, s44, 0x80080
	s_addc_u32 s45, s45, 0
	s_add_i32 s46, s60, s31
	global_load_lds_dwordx4 v182, s[98:99]
	s_mov_b32 m0, s46
	s_nop 0
	global_load_lds_dwordx4 v178, s[44:45]
	s_add_i32 m0, s46, 0x2000
	s_nop 0
	global_load_lds_dwordx4 v182, s[44:45]
	s_mov_b32 m0, s52
	s_nop 0
	global_load_lds_dwordx4 v176, s[100:101]
	s_mov_b32 m0, s53
	s_nop 0
	global_load_lds_dwordx4 v180, s[100:101]
	s_waitcnt vmcnt(8)
	s_waitcnt lgkmcnt(0)
	s_setprio 1
	s_barrier
	v_mfma_f32_16x16x32_bf16 v[60:63], v[128:131], v[160:163], v[60:63]
	v_mfma_f32_16x16x32_bf16 v[56:59], v[136:139], v[160:163], v[56:59]
	v_mfma_f32_16x16x32_bf16 v[44:47], v[128:131], v[168:171], v[44:47]
	v_mfma_f32_16x16x32_bf16 v[40:43], v[136:139], v[168:171], v[40:43]
	v_mfma_f32_16x16x32_bf16 v[28:31], v[128:131], v[192:195], v[28:31]
	v_mfma_f32_16x16x32_bf16 v[24:27], v[136:139], v[192:195], v[24:27]
	v_mfma_f32_16x16x32_bf16 v[12:15], v[128:131], v[200:203], v[12:15]
	v_mfma_f32_16x16x32_bf16 v[8:11], v[136:139], v[200:203], v[8:11]
	v_mfma_f32_16x16x32_bf16 v[60:63], v[132:135], v[164:167], v[60:63]
	v_mfma_f32_16x16x32_bf16 v[56:59], v[140:143], v[164:167], v[56:59]
	v_mfma_f32_16x16x32_bf16 v[44:47], v[132:135], v[172:175], v[44:47]
	v_mfma_f32_16x16x32_bf16 v[40:43], v[140:143], v[172:175], v[40:43]
	v_mfma_f32_16x16x32_bf16 v[28:31], v[132:135], v[196:199], v[28:31]
	v_mfma_f32_16x16x32_bf16 v[24:27], v[140:143], v[196:199], v[24:27]
	v_mfma_f32_16x16x32_bf16 v[12:15], v[132:135], v[204:207], v[12:15]
	v_mfma_f32_16x16x32_bf16 v[8:11], v[140:143], v[204:207], v[8:11]
	s_setprio 0
	s_setprio 1
	v_mfma_f32_16x16x32_bf16 v[52:55], v[144:147], v[160:163], v[52:55]
	v_mfma_f32_16x16x32_bf16 v[48:51], v[152:155], v[160:163], v[48:51]
	v_mfma_f32_16x16x32_bf16 v[36:39], v[144:147], v[168:171], v[36:39]
	v_mfma_f32_16x16x32_bf16 v[32:35], v[152:155], v[168:171], v[32:35]
	v_mfma_f32_16x16x32_bf16 v[20:23], v[144:147], v[192:195], v[20:23]
	v_mfma_f32_16x16x32_bf16 v[16:19], v[152:155], v[192:195], v[16:19]
	v_mfma_f32_16x16x32_bf16 v[4:7], v[144:147], v[200:203], v[4:7]
	v_mfma_f32_16x16x32_bf16 v[0:3], v[152:155], v[200:203], v[0:3]
	v_mfma_f32_16x16x32_bf16 v[52:55], v[148:151], v[164:167], v[52:55]
	v_mfma_f32_16x16x32_bf16 v[48:51], v[156:159], v[164:167], v[48:51]
	v_mfma_f32_16x16x32_bf16 v[36:39], v[148:151], v[172:175], v[36:39]
	v_mfma_f32_16x16x32_bf16 v[32:35], v[156:159], v[172:175], v[32:35]
	v_mfma_f32_16x16x32_bf16 v[20:23], v[148:151], v[196:199], v[20:23]
	v_mfma_f32_16x16x32_bf16 v[16:19], v[156:159], v[196:199], v[16:19]
	v_mfma_f32_16x16x32_bf16 v[4:7], v[148:151], v[204:207], v[4:7]
	v_mfma_f32_16x16x32_bf16 v[0:3], v[156:159], v[204:207], v[0:3]
	s_setprio 0
	s_barrier
	s_add_i32 s58, s58, 2
	s_add_u32 s42, s42, 0x100
	s_addc_u32 s43, s43, 0
	s_add_u32 s25, s25, 0x100
	s_addc_u32 s35, s35, 0
	s_cmp_gt_u32 s58, 29
.LBB0_543:
	ds_read_b128 v[128:131], v216
	ds_read_b128 v[132:135], v216 offset:1024
	ds_read_b128 v[136:139], v216 offset:2048
	ds_read_b128 v[140:143], v216 offset:3072
	ds_read_b128 v[144:147], v217
	ds_read_b128 v[148:151], v217 offset:1024
	ds_read_b128 v[152:155], v217 offset:2048
	ds_read_b128 v[156:159], v217 offset:3072
	s_add_u32 s44, s42, 0xfff80080
	s_addc_u32 s45, s43, -1
	s_cmp_eq_u32 s58, 28
	s_cselect_b32 s47, s0, s45
	s_cselect_b32 s46, s1, s44
	s_cselect_b32 s45, s3, s35
	s_cselect_b32 s44, s9, s25
	s_add_i32 m0, s41, 0xc000
	ds_read_b128 v[160:163], v218
	ds_read_b128 v[164:167], v218 offset:1024
	ds_read_b128 v[168:171], v218 offset:2048
	ds_read_b128 v[172:175], v218 offset:3072
	ds_read_b128 v[192:195], v218 offset:4096
	ds_read_b128 v[196:199], v218 offset:5120
	ds_read_b128 v[200:203], v218 offset:6144
	ds_read_b128 v[204:207], v218 offset:7168
	global_load_lds_dwordx4 v184, s[42:43]
	s_add_i32 m0, s41, 0xe000
	s_nop 0
	global_load_lds_dwordx4 v186, s[42:43]
	s_waitcnt vmcnt(8)
	s_waitcnt lgkmcnt(0)
	s_setprio 1
	s_barrier
	v_mfma_f32_16x16x32_bf16 v[124:127], v[128:131], v[160:163], v[124:127]
	v_mfma_f32_16x16x32_bf16 v[120:123], v[136:139], v[160:163], v[120:123]
	v_mfma_f32_16x16x32_bf16 v[108:111], v[128:131], v[168:171], v[108:111]
	v_mfma_f32_16x16x32_bf16 v[104:107], v[136:139], v[168:171], v[104:107]
	v_mfma_f32_16x16x32_bf16 v[92:95], v[128:131], v[192:195], v[92:95]
	v_mfma_f32_16x16x32_bf16 v[88:91], v[136:139], v[192:195], v[88:91]
	v_mfma_f32_16x16x32_bf16 v[76:79], v[128:131], v[200:203], v[76:79]
	v_mfma_f32_16x16x32_bf16 v[72:75], v[136:139], v[200:203], v[72:75]
	v_mfma_f32_16x16x32_bf16 v[124:127], v[132:135], v[164:167], v[124:127]
	v_mfma_f32_16x16x32_bf16 v[120:123], v[140:143], v[164:167], v[120:123]
	v_mfma_f32_16x16x32_bf16 v[108:111], v[132:135], v[172:175], v[108:111]
	v_mfma_f32_16x16x32_bf16 v[104:107], v[140:143], v[172:175], v[104:107]
	v_mfma_f32_16x16x32_bf16 v[92:95], v[132:135], v[196:199], v[92:95]
	v_mfma_f32_16x16x32_bf16 v[88:91], v[140:143], v[196:199], v[88:91]
	v_mfma_f32_16x16x32_bf16 v[76:79], v[132:135], v[204:207], v[76:79]
	v_mfma_f32_16x16x32_bf16 v[72:75], v[140:143], v[204:207], v[72:75]
	s_setprio 0
	s_setprio 1
	v_mfma_f32_16x16x32_bf16 v[116:119], v[144:147], v[160:163], v[116:119]
	v_mfma_f32_16x16x32_bf16 v[112:115], v[152:155], v[160:163], v[112:115]
	v_mfma_f32_16x16x32_bf16 v[100:103], v[144:147], v[168:171], v[100:103]
	v_mfma_f32_16x16x32_bf16 v[96:99], v[152:155], v[168:171], v[96:99]
	v_mfma_f32_16x16x32_bf16 v[84:87], v[144:147], v[192:195], v[84:87]
	v_mfma_f32_16x16x32_bf16 v[80:83], v[152:155], v[192:195], v[80:83]
	v_mfma_f32_16x16x32_bf16 v[68:71], v[144:147], v[200:203], v[68:71]
	v_mfma_f32_16x16x32_bf16 v[64:67], v[152:155], v[200:203], v[64:67]
	v_mfma_f32_16x16x32_bf16 v[116:119], v[148:151], v[164:167], v[116:119]
	v_mfma_f32_16x16x32_bf16 v[112:115], v[156:159], v[164:167], v[112:115]
	v_mfma_f32_16x16x32_bf16 v[100:103], v[148:151], v[172:175], v[100:103]
	v_mfma_f32_16x16x32_bf16 v[96:99], v[156:159], v[172:175], v[96:99]
	v_mfma_f32_16x16x32_bf16 v[84:87], v[148:151], v[196:199], v[84:87]
	v_mfma_f32_16x16x32_bf16 v[80:83], v[156:159], v[196:199], v[80:83]
	v_mfma_f32_16x16x32_bf16 v[68:71], v[148:151], v[204:207], v[68:71]
	v_mfma_f32_16x16x32_bf16 v[64:67], v[156:159], v[204:207], v[64:67]
	s_setprio 0
	s_barrier
	s_add_i32 s59, s55, s31
	s_add_u32 s98, s44, s20
	s_addc_u32 s99, s45, s21
	s_mov_b32 m0, s59
	ds_read_b128 v[160:163], v218 offset:16384
	ds_read_b128 v[164:167], v218 offset:17408
	ds_read_b128 v[168:171], v218 offset:18432
	ds_read_b128 v[172:175], v218 offset:19456
	ds_read_b128 v[192:195], v218 offset:20480
	ds_read_b128 v[196:199], v218 offset:21504
	ds_read_b128 v[200:203], v218 offset:22528
	ds_read_b128 v[204:207], v218 offset:23552
	global_load_lds_dwordx4 v178, s[44:45]
	s_add_i32 m0, s59, 0x2000
	s_add_u32 s60, s44, 0x80000
	s_addc_u32 s61, s45, 0
	s_add_i32 s59, s56, s31
	global_load_lds_dwordx4 v182, s[44:45]
	s_mov_b32 m0, s59
	s_add_u32 s100, s46, s20
	s_addc_u32 s101, s47, s21
	global_load_lds_dwordx4 v178, s[60:61]
	s_add_i32 m0, s59, 0x2000
	s_nop 0
	global_load_lds_dwordx4 v182, s[60:61]
	s_mov_b32 m0, s41
	s_nop 0
	global_load_lds_dwordx4 v176, s[46:47]
	s_mov_b32 m0, s48
	s_nop 0
	global_load_lds_dwordx4 v180, s[46:47]
	s_waitcnt vmcnt(8)
	s_waitcnt lgkmcnt(0)
	s_setprio 1
	s_barrier
	v_mfma_f32_16x16x32_bf16 v[60:63], v[128:131], v[160:163], v[60:63]
	v_mfma_f32_16x16x32_bf16 v[56:59], v[136:139], v[160:163], v[56:59]
	v_mfma_f32_16x16x32_bf16 v[44:47], v[128:131], v[168:171], v[44:47]
	v_mfma_f32_16x16x32_bf16 v[40:43], v[136:139], v[168:171], v[40:43]
	v_mfma_f32_16x16x32_bf16 v[28:31], v[128:131], v[192:195], v[28:31]
	v_mfma_f32_16x16x32_bf16 v[24:27], v[136:139], v[192:195], v[24:27]
	v_mfma_f32_16x16x32_bf16 v[12:15], v[128:131], v[200:203], v[12:15]
	v_mfma_f32_16x16x32_bf16 v[8:11], v[136:139], v[200:203], v[8:11]
	v_mfma_f32_16x16x32_bf16 v[60:63], v[132:135], v[164:167], v[60:63]
	v_mfma_f32_16x16x32_bf16 v[56:59], v[140:143], v[164:167], v[56:59]
	v_mfma_f32_16x16x32_bf16 v[44:47], v[132:135], v[172:175], v[44:47]
	v_mfma_f32_16x16x32_bf16 v[40:43], v[140:143], v[172:175], v[40:43]
	v_mfma_f32_16x16x32_bf16 v[28:31], v[132:135], v[196:199], v[28:31]
	v_mfma_f32_16x16x32_bf16 v[24:27], v[140:143], v[196:199], v[24:27]
	v_mfma_f32_16x16x32_bf16 v[12:15], v[132:135], v[204:207], v[12:15]
	v_mfma_f32_16x16x32_bf16 v[8:11], v[140:143], v[204:207], v[8:11]
	s_setprio 0
	s_setprio 1
	v_mfma_f32_16x16x32_bf16 v[52:55], v[144:147], v[160:163], v[52:55]
	v_mfma_f32_16x16x32_bf16 v[48:51], v[152:155], v[160:163], v[48:51]
	v_mfma_f32_16x16x32_bf16 v[36:39], v[144:147], v[168:171], v[36:39]
	v_mfma_f32_16x16x32_bf16 v[32:35], v[152:155], v[168:171], v[32:35]
	v_mfma_f32_16x16x32_bf16 v[20:23], v[144:147], v[192:195], v[20:23]
	v_mfma_f32_16x16x32_bf16 v[16:19], v[152:155], v[192:195], v[16:19]
	v_mfma_f32_16x16x32_bf16 v[4:7], v[144:147], v[200:203], v[4:7]
	v_mfma_f32_16x16x32_bf16 v[0:3], v[152:155], v[200:203], v[0:3]
	v_mfma_f32_16x16x32_bf16 v[52:55], v[148:151], v[164:167], v[52:55]
	v_mfma_f32_16x16x32_bf16 v[48:51], v[156:159], v[164:167], v[48:51]
	v_mfma_f32_16x16x32_bf16 v[36:39], v[148:151], v[172:175], v[36:39]
	v_mfma_f32_16x16x32_bf16 v[32:35], v[156:159], v[172:175], v[32:35]
	v_mfma_f32_16x16x32_bf16 v[20:23], v[148:151], v[196:199], v[20:23]
	v_mfma_f32_16x16x32_bf16 v[16:19], v[156:159], v[196:199], v[16:19]
	v_mfma_f32_16x16x32_bf16 v[4:7], v[148:151], v[204:207], v[4:7]
	v_mfma_f32_16x16x32_bf16 v[0:3], v[156:159], v[204:207], v[0:3]
	s_setprio 0
	s_barrier
	s_add_i32 s59, 0, 0x18000
	s_add_i32 s60, 0, 0x1c000
	v_add_u32_e32 v140, s59, v214
	v_add_u32_e32 v156, s60, v214
	ds_read_b128 v[128:131], v140
	ds_read_b128 v[132:135], v140 offset:1024
	ds_read_b128 v[136:139], v140 offset:2048
	ds_read_b128 v[140:143], v140 offset:3072
	ds_read_b128 v[144:147], v156
	ds_read_b128 v[148:151], v156 offset:1024
	ds_read_b128 v[152:155], v156 offset:2048
	ds_read_b128 v[156:159], v156 offset:3072
	s_add_u32 s46, s46, 0x80000
	s_addc_u32 s47, s47, 0
	s_mov_b32 m0, s49
	ds_read_b128 v[160:163], v218 offset:32768
	ds_read_b128 v[164:167], v218 offset:33792
	ds_read_b128 v[168:171], v218 offset:34816
	ds_read_b128 v[172:175], v218 offset:35840
	ds_read_b128 v[192:195], v218 offset:36864
	ds_read_b128 v[196:199], v218 offset:37888
	ds_read_b128 v[200:203], v218 offset:38912
	ds_read_b128 v[204:207], v218 offset:39936
	global_load_lds_dwordx4 v176, s[46:47]
	s_mov_b32 m0, s50
	s_nop 0
	global_load_lds_dwordx4 v180, s[46:47]
	s_waitcnt vmcnt(8)
	s_waitcnt lgkmcnt(0)
	s_setprio 1
	s_barrier
	v_mfma_f32_16x16x32_bf16 v[124:127], v[128:131], v[160:163], v[124:127]
	v_mfma_f32_16x16x32_bf16 v[120:123], v[136:139], v[160:163], v[120:123]
	v_mfma_f32_16x16x32_bf16 v[108:111], v[128:131], v[168:171], v[108:111]
	v_mfma_f32_16x16x32_bf16 v[104:107], v[136:139], v[168:171], v[104:107]
	v_mfma_f32_16x16x32_bf16 v[92:95], v[128:131], v[192:195], v[92:95]
	v_mfma_f32_16x16x32_bf16 v[88:91], v[136:139], v[192:195], v[88:91]
	v_mfma_f32_16x16x32_bf16 v[76:79], v[128:131], v[200:203], v[76:79]
	v_mfma_f32_16x16x32_bf16 v[72:75], v[136:139], v[200:203], v[72:75]
	v_mfma_f32_16x16x32_bf16 v[124:127], v[132:135], v[164:167], v[124:127]
	v_mfma_f32_16x16x32_bf16 v[120:123], v[140:143], v[164:167], v[120:123]
	v_mfma_f32_16x16x32_bf16 v[108:111], v[132:135], v[172:175], v[108:111]
	v_mfma_f32_16x16x32_bf16 v[104:107], v[140:143], v[172:175], v[104:107]
	v_mfma_f32_16x16x32_bf16 v[92:95], v[132:135], v[196:199], v[92:95]
	v_mfma_f32_16x16x32_bf16 v[88:91], v[140:143], v[196:199], v[88:91]
	v_mfma_f32_16x16x32_bf16 v[76:79], v[132:135], v[204:207], v[76:79]
	v_mfma_f32_16x16x32_bf16 v[72:75], v[140:143], v[204:207], v[72:75]
	s_setprio 0
	s_setprio 1
	v_mfma_f32_16x16x32_bf16 v[116:119], v[144:147], v[160:163], v[116:119]
	v_mfma_f32_16x16x32_bf16 v[112:115], v[152:155], v[160:163], v[112:115]
	v_mfma_f32_16x16x32_bf16 v[100:103], v[144:147], v[168:171], v[100:103]
	v_mfma_f32_16x16x32_bf16 v[96:99], v[152:155], v[168:171], v[96:99]
	v_mfma_f32_16x16x32_bf16 v[84:87], v[144:147], v[192:195], v[84:87]
	v_mfma_f32_16x16x32_bf16 v[80:83], v[152:155], v[192:195], v[80:83]
	v_mfma_f32_16x16x32_bf16 v[68:71], v[144:147], v[200:203], v[68:71]
	v_mfma_f32_16x16x32_bf16 v[64:67], v[152:155], v[200:203], v[64:67]
	v_mfma_f32_16x16x32_bf16 v[116:119], v[148:151], v[164:167], v[116:119]
	v_mfma_f32_16x16x32_bf16 v[112:115], v[156:159], v[164:167], v[112:115]
	v_mfma_f32_16x16x32_bf16 v[100:103], v[148:151], v[172:175], v[100:103]
	v_mfma_f32_16x16x32_bf16 v[96:99], v[156:159], v[172:175], v[96:99]
	v_mfma_f32_16x16x32_bf16 v[84:87], v[148:151], v[196:199], v[84:87]
	v_mfma_f32_16x16x32_bf16 v[80:83], v[156:159], v[196:199], v[80:83]
	v_mfma_f32_16x16x32_bf16 v[68:71], v[148:151], v[204:207], v[68:71]
	v_mfma_f32_16x16x32_bf16 v[64:67], v[156:159], v[204:207], v[64:67]
	s_setprio 0
	s_barrier
	s_add_i32 s46, s59, s31
	s_mov_b32 m0, s46
	ds_read_b128 v[160:163], v218 offset:49152
	ds_read_b128 v[164:167], v218 offset:50176
	ds_read_b128 v[168:171], v218 offset:51200
	ds_read_b128 v[172:175], v218 offset:52224
	ds_read_b128 v[192:195], v218 offset:53248
	ds_read_b128 v[196:199], v218 offset:54272
	ds_read_b128 v[200:203], v218 offset:55296
	ds_read_b128 v[204:207], v218 offset:56320
	global_load_lds_dwordx4 v178, s[98:99]
	s_add_i32 m0, s46, 0x2000
	s_add_u32 s44, s44, 0x80080
	s_addc_u32 s45, s45, 0
	s_add_i32 s46, s60, s31
	global_load_lds_dwordx4 v182, s[98:99]
	s_mov_b32 m0, s46
	s_nop 0
	global_load_lds_dwordx4 v178, s[44:45]
	s_add_i32 m0, s46, 0x2000
	s_nop 0
	global_load_lds_dwordx4 v182, s[44:45]
	s_mov_b32 m0, s52
	s_nop 0
	global_load_lds_dwordx4 v176, s[100:101]
	s_mov_b32 m0, s53
	s_nop 0
	global_load_lds_dwordx4 v180, s[100:101]
	s_waitcnt vmcnt(8)
	s_waitcnt lgkmcnt(0)
	s_setprio 1
	s_barrier
	v_mfma_f32_16x16x32_bf16 v[60:63], v[128:131], v[160:163], v[60:63]
	v_mfma_f32_16x16x32_bf16 v[56:59], v[136:139], v[160:163], v[56:59]
	v_mfma_f32_16x16x32_bf16 v[44:47], v[128:131], v[168:171], v[44:47]
	v_mfma_f32_16x16x32_bf16 v[40:43], v[136:139], v[168:171], v[40:43]
	v_mfma_f32_16x16x32_bf16 v[28:31], v[128:131], v[192:195], v[28:31]
	v_mfma_f32_16x16x32_bf16 v[24:27], v[136:139], v[192:195], v[24:27]
	v_mfma_f32_16x16x32_bf16 v[12:15], v[128:131], v[200:203], v[12:15]
	v_mfma_f32_16x16x32_bf16 v[8:11], v[136:139], v[200:203], v[8:11]
	v_mfma_f32_16x16x32_bf16 v[60:63], v[132:135], v[164:167], v[60:63]
	v_mfma_f32_16x16x32_bf16 v[56:59], v[140:143], v[164:167], v[56:59]
	v_mfma_f32_16x16x32_bf16 v[44:47], v[132:135], v[172:175], v[44:47]
	v_mfma_f32_16x16x32_bf16 v[40:43], v[140:143], v[172:175], v[40:43]
	v_mfma_f32_16x16x32_bf16 v[28:31], v[132:135], v[196:199], v[28:31]
	v_mfma_f32_16x16x32_bf16 v[24:27], v[140:143], v[196:199], v[24:27]
	v_mfma_f32_16x16x32_bf16 v[12:15], v[132:135], v[204:207], v[12:15]
	v_mfma_f32_16x16x32_bf16 v[8:11], v[140:143], v[204:207], v[8:11]
	s_setprio 0
	s_setprio 1
	v_mfma_f32_16x16x32_bf16 v[52:55], v[144:147], v[160:163], v[52:55]
	v_mfma_f32_16x16x32_bf16 v[48:51], v[152:155], v[160:163], v[48:51]
	v_mfma_f32_16x16x32_bf16 v[36:39], v[144:147], v[168:171], v[36:39]
	v_mfma_f32_16x16x32_bf16 v[32:35], v[152:155], v[168:171], v[32:35]
	v_mfma_f32_16x16x32_bf16 v[20:23], v[144:147], v[192:195], v[20:23]
	v_mfma_f32_16x16x32_bf16 v[16:19], v[152:155], v[192:195], v[16:19]
	v_mfma_f32_16x16x32_bf16 v[4:7], v[144:147], v[200:203], v[4:7]
	v_mfma_f32_16x16x32_bf16 v[0:3], v[152:155], v[200:203], v[0:3]
	v_mfma_f32_16x16x32_bf16 v[52:55], v[148:151], v[164:167], v[52:55]
	v_mfma_f32_16x16x32_bf16 v[48:51], v[156:159], v[164:167], v[48:51]
	v_mfma_f32_16x16x32_bf16 v[36:39], v[148:151], v[172:175], v[36:39]
	v_mfma_f32_16x16x32_bf16 v[32:35], v[156:159], v[172:175], v[32:35]
	v_mfma_f32_16x16x32_bf16 v[20:23], v[148:151], v[196:199], v[20:23]
	v_mfma_f32_16x16x32_bf16 v[16:19], v[156:159], v[196:199], v[16:19]
	v_mfma_f32_16x16x32_bf16 v[4:7], v[148:151], v[204:207], v[4:7]
	v_mfma_f32_16x16x32_bf16 v[0:3], v[156:159], v[204:207], v[0:3]
	s_setprio 0
	s_barrier
	s_add_i32 s58, s58, 2
	s_add_u32 s42, s42, 0x100
	s_addc_u32 s43, s43, 0
	s_add_u32 s25, s25, 0x100
	s_addc_u32 s35, s35, 0
	s_cmp_gt_u32 s58, 29
	s_cbranch_scc0 .LBB0_543
	s_and_b64 vcc, exec, s[22:23]
	s_cbranch_vccz .LBB0_546
	s_barrier

.LBB0_635:
	s_ashr_i32 s67, s66, 31
	s_lshl_b64 s[12:13], s[66:67], 20
	s_add_u32 s70, s55, s12
	s_addc_u32 s71, s57, s13
	s_and_b64 s[6:7], s[6:7], exec
	s_cselect_b32 s1, s71, s11
	s_cselect_b32 s3, s70, s10
	s_add_u32 s6, s8, 0x80080
	s_addc_u32 s7, s9, 0
	s_add_u32 s12, s10, 0x100
	s_addc_u32 s13, s11, 0
	s_mov_b32 s15, -2
	s_waitcnt vmcnt(0)
	ds_read_b128 v[148:151], v197
	ds_read_b128 v[170:173], v197 offset:1024
	ds_read_b128 v[174:177], v197 offset:2048
	ds_read_b128 v[178:181], v197 offset:3072
	ds_read_b128 v[182:185], v198
	ds_read_b128 v[186:189], v198 offset:1024
	ds_read_b128 v[202:205], v198 offset:2048
	ds_read_b128 v[206:209], v198 offset:3072
	s_add_u32 s8, s6, 0xfff80080
	s_addc_u32 s9, s7, -1
	s_cmp_eq_u32 s15, 28
	s_cselect_b32 s11, s69, s9
	s_cselect_b32 s10, s68, s8
	s_cselect_b32 s9, s1, s13
	s_cselect_b32 s8, s3, s12
	s_add_i32 m0, s72, 0xc000
	ds_read_b128 v[214:217], v199
	ds_read_b128 v[218:221], v199 offset:1024
	ds_read_b128 v[222:225], v199 offset:2048
	ds_read_b128 v[226:229], v199 offset:3072
	ds_read_b128 v[230:233], v199 offset:4096
	ds_read_b128 v[234:237], v199 offset:5120
	ds_read_b128 v[238:241], v199 offset:6144
	ds_read_b128 v[242:245], v199 offset:7168
	global_load_lds_dwordx4 v162, s[6:7]
	s_add_i32 m0, s72, 0xe000
	s_nop 0
	global_load_lds_dwordx4 v164, s[6:7]
	s_waitcnt vmcnt(8)
	s_waitcnt lgkmcnt(0)
	s_setprio 1
	s_barrier
	v_mfma_f32_16x16x32_bf16 v[112:115], v[148:151], v[214:217], 0
	v_mfma_f32_16x16x32_bf16 v[80:83], v[174:177], v[214:217], 0
	v_mfma_f32_16x16x32_bf16 v[116:119], v[148:151], v[222:225], 0
	v_mfma_f32_16x16x32_bf16 v[88:91], v[174:177], v[222:225], 0
	v_mfma_f32_16x16x32_bf16 v[124:127], v[148:151], v[230:233], 0
	v_mfma_f32_16x16x32_bf16 v[92:95], v[174:177], v[230:233], 0
	v_mfma_f32_16x16x32_bf16 v[120:123], v[148:151], v[238:241], 0
	v_mfma_f32_16x16x32_bf16 v[84:87], v[174:177], v[238:241], 0
	v_mfma_f32_16x16x32_bf16 v[112:115], v[170:173], v[218:221], v[112:115]
	v_mfma_f32_16x16x32_bf16 v[80:83], v[178:181], v[218:221], v[80:83]
	v_mfma_f32_16x16x32_bf16 v[116:119], v[170:173], v[226:229], v[116:119]
	v_mfma_f32_16x16x32_bf16 v[88:91], v[178:181], v[226:229], v[88:91]
	v_mfma_f32_16x16x32_bf16 v[124:127], v[170:173], v[234:237], v[124:127]
	v_mfma_f32_16x16x32_bf16 v[92:95], v[178:181], v[234:237], v[92:95]
	v_mfma_f32_16x16x32_bf16 v[120:123], v[170:173], v[242:245], v[120:123]
	v_mfma_f32_16x16x32_bf16 v[84:87], v[178:181], v[242:245], v[84:87]
	s_setprio 0
	s_setprio 1
	v_mfma_f32_16x16x32_bf16 v[108:111], v[182:185], v[214:217], 0
	v_mfma_f32_16x16x32_bf16 v[76:79], v[202:205], v[214:217], 0
	v_mfma_f32_16x16x32_bf16 v[104:107], v[182:185], v[222:225], 0
	v_mfma_f32_16x16x32_bf16 v[72:75], v[202:205], v[222:225], 0
	v_mfma_f32_16x16x32_bf16 v[100:103], v[182:185], v[230:233], 0
	v_mfma_f32_16x16x32_bf16 v[68:71], v[202:205], v[230:233], 0
	v_mfma_f32_16x16x32_bf16 v[96:99], v[182:185], v[238:241], 0
	v_mfma_f32_16x16x32_bf16 v[64:67], v[202:205], v[238:241], 0
	v_mfma_f32_16x16x32_bf16 v[108:111], v[186:189], v[218:221], v[108:111]
	v_mfma_f32_16x16x32_bf16 v[76:79], v[206:209], v[218:221], v[76:79]
	v_mfma_f32_16x16x32_bf16 v[104:107], v[186:189], v[226:229], v[104:107]
	v_mfma_f32_16x16x32_bf16 v[72:75], v[206:209], v[226:229], v[72:75]
	v_mfma_f32_16x16x32_bf16 v[100:103], v[186:189], v[234:237], v[100:103]
	v_mfma_f32_16x16x32_bf16 v[68:71], v[206:209], v[234:237], v[68:71]
	v_mfma_f32_16x16x32_bf16 v[96:99], v[186:189], v[242:245], v[96:99]
	v_mfma_f32_16x16x32_bf16 v[64:67], v[206:209], v[242:245], v[64:67]
	s_setprio 0
	s_barrier
	s_add_i32 s16, s94, s63
	s_add_u32 s98, s8, s40
	s_addc_u32 s99, s9, s41
	s_mov_b32 m0, s16
	ds_read_b128 v[214:217], v199 offset:16384
	ds_read_b128 v[218:221], v199 offset:17408
	ds_read_b128 v[222:225], v199 offset:18432
	ds_read_b128 v[226:229], v199 offset:19456
	ds_read_b128 v[230:233], v199 offset:20480
	ds_read_b128 v[234:237], v199 offset:21504
	ds_read_b128 v[238:241], v199 offset:22528
	ds_read_b128 v[242:245], v199 offset:23552
	global_load_lds_dwordx4 v154, s[8:9]
	s_add_i32 m0, s16, 0x2000
	s_add_u32 s16, s8, 0x80000
	s_addc_u32 s17, s9, 0
	s_add_i32 s18, s95, s63
	global_load_lds_dwordx4 v158, s[8:9]
	s_mov_b32 m0, s18
	s_add_u32 s100, s10, s40
	s_addc_u32 s101, s11, s41
	global_load_lds_dwordx4 v154, s[16:17]
	s_add_i32 m0, s18, 0x2000
	s_nop 0
	global_load_lds_dwordx4 v158, s[16:17]
	s_mov_b32 m0, s72
	s_nop 0
	global_load_lds_dwordx4 v152, s[10:11]
	s_mov_b32 m0, s73
	s_nop 0
	global_load_lds_dwordx4 v156, s[10:11]
	s_waitcnt vmcnt(8)
	s_waitcnt lgkmcnt(0)
	s_setprio 1
	s_barrier
	v_mfma_f32_16x16x32_bf16 v[48:51], v[148:151], v[214:217], 0
	v_mfma_f32_16x16x32_bf16 v[16:19], v[174:177], v[214:217], 0
	v_mfma_f32_16x16x32_bf16 v[52:55], v[148:151], v[222:225], 0
	v_mfma_f32_16x16x32_bf16 v[24:27], v[174:177], v[222:225], 0
	v_mfma_f32_16x16x32_bf16 v[60:63], v[148:151], v[230:233], 0
	v_mfma_f32_16x16x32_bf16 v[28:31], v[174:177], v[230:233], 0
	v_mfma_f32_16x16x32_bf16 v[56:59], v[148:151], v[238:241], 0
	v_mfma_f32_16x16x32_bf16 v[20:23], v[174:177], v[238:241], 0
	v_mfma_f32_16x16x32_bf16 v[48:51], v[170:173], v[218:221], v[48:51]
	v_mfma_f32_16x16x32_bf16 v[16:19], v[178:181], v[218:221], v[16:19]
	v_mfma_f32_16x16x32_bf16 v[52:55], v[170:173], v[226:229], v[52:55]
	v_mfma_f32_16x16x32_bf16 v[24:27], v[178:181], v[226:229], v[24:27]
	v_mfma_f32_16x16x32_bf16 v[60:63], v[170:173], v[234:237], v[60:63]
	v_mfma_f32_16x16x32_bf16 v[28:31], v[178:181], v[234:237], v[28:31]
	v_mfma_f32_16x16x32_bf16 v[56:59], v[170:173], v[242:245], v[56:59]
	v_mfma_f32_16x16x32_bf16 v[20:23], v[178:181], v[242:245], v[20:23]
	s_setprio 0
	s_setprio 1
	v_mfma_f32_16x16x32_bf16 v[44:47], v[182:185], v[214:217], 0
	v_mfma_f32_16x16x32_bf16 v[12:15], v[202:205], v[214:217], 0
	v_mfma_f32_16x16x32_bf16 v[40:43], v[182:185], v[222:225], 0
	v_mfma_f32_16x16x32_bf16 v[8:11], v[202:205], v[222:225], 0
	v_mfma_f32_16x16x32_bf16 v[36:39], v[182:185], v[230:233], 0
	v_mfma_f32_16x16x32_bf16 v[4:7], v[202:205], v[230:233], 0
	v_mfma_f32_16x16x32_bf16 v[32:35], v[182:185], v[238:241], 0
	v_mfma_f32_16x16x32_bf16 v[0:3], v[202:205], v[238:241], 0
	v_mfma_f32_16x16x32_bf16 v[44:47], v[186:189], v[218:221], v[44:47]
	v_mfma_f32_16x16x32_bf16 v[12:15], v[206:209], v[218:221], v[12:15]
	v_mfma_f32_16x16x32_bf16 v[40:43], v[186:189], v[226:229], v[40:43]
	v_mfma_f32_16x16x32_bf16 v[8:11], v[206:209], v[226:229], v[8:11]
	v_mfma_f32_16x16x32_bf16 v[36:39], v[186:189], v[234:237], v[36:39]
	v_mfma_f32_16x16x32_bf16 v[4:7], v[206:209], v[234:237], v[4:7]
	v_mfma_f32_16x16x32_bf16 v[32:35], v[186:189], v[242:245], v[32:35]
	v_mfma_f32_16x16x32_bf16 v[0:3], v[206:209], v[242:245], v[0:3]
	s_setprio 0
	s_barrier
	s_add_i32 s16, 0, 0x18000
	s_add_i32 s17, 0, 0x1c000
	v_add_u32_e32 v178, s16, v196
	v_add_u32_e32 v201, s17, v196
	ds_read_b128 v[148:151], v178
	ds_read_b128 v[170:173], v178 offset:1024
	ds_read_b128 v[174:177], v178 offset:2048
	ds_read_b128 v[178:181], v178 offset:3072
	ds_read_b128 v[182:185], v201
	ds_read_b128 v[186:189], v201 offset:1024
	ds_read_b128 v[202:205], v201 offset:2048
	ds_read_b128 v[206:209], v201 offset:3072
	s_add_u32 s10, s10, 0x80000
	s_addc_u32 s11, s11, 0
	s_mov_b32 m0, s74
	ds_read_b128 v[214:217], v199 offset:32768
	ds_read_b128 v[218:221], v199 offset:33792
	ds_read_b128 v[222:225], v199 offset:34816
	ds_read_b128 v[226:229], v199 offset:35840
	ds_read_b128 v[230:233], v199 offset:36864
	ds_read_b128 v[234:237], v199 offset:37888
	ds_read_b128 v[238:241], v199 offset:38912
	ds_read_b128 v[242:245], v199 offset:39936
	global_load_lds_dwordx4 v152, s[10:11]
	s_mov_b32 m0, s75
	s_nop 0
	global_load_lds_dwordx4 v156, s[10:11]
	s_waitcnt vmcnt(8)
	s_waitcnt lgkmcnt(0)
	s_setprio 1
	s_barrier
	v_mfma_f32_16x16x32_bf16 v[112:115], v[148:151], v[214:217], v[112:115]
	v_mfma_f32_16x16x32_bf16 v[80:83], v[174:177], v[214:217], v[80:83]
	v_mfma_f32_16x16x32_bf16 v[116:119], v[148:151], v[222:225], v[116:119]
	v_mfma_f32_16x16x32_bf16 v[88:91], v[174:177], v[222:225], v[88:91]
	v_mfma_f32_16x16x32_bf16 v[124:127], v[148:151], v[230:233], v[124:127]
	v_mfma_f32_16x16x32_bf16 v[92:95], v[174:177], v[230:233], v[92:95]
	v_mfma_f32_16x16x32_bf16 v[120:123], v[148:151], v[238:241], v[120:123]
	v_mfma_f32_16x16x32_bf16 v[84:87], v[174:177], v[238:241], v[84:87]
	v_mfma_f32_16x16x32_bf16 v[112:115], v[170:173], v[218:221], v[112:115]
	v_mfma_f32_16x16x32_bf16 v[80:83], v[178:181], v[218:221], v[80:83]
	v_mfma_f32_16x16x32_bf16 v[116:119], v[170:173], v[226:229], v[116:119]
	v_mfma_f32_16x16x32_bf16 v[88:91], v[178:181], v[226:229], v[88:91]
	v_mfma_f32_16x16x32_bf16 v[124:127], v[170:173], v[234:237], v[124:127]
	v_mfma_f32_16x16x32_bf16 v[92:95], v[178:181], v[234:237], v[92:95]
	v_mfma_f32_16x16x32_bf16 v[120:123], v[170:173], v[242:245], v[120:123]
	v_mfma_f32_16x16x32_bf16 v[84:87], v[178:181], v[242:245], v[84:87]
	s_setprio 0
	s_setprio 1
	v_mfma_f32_16x16x32_bf16 v[108:111], v[182:185], v[214:217], v[108:111]
	v_mfma_f32_16x16x32_bf16 v[76:79], v[202:205], v[214:217], v[76:79]
	v_mfma_f32_16x16x32_bf16 v[104:107], v[182:185], v[222:225], v[104:107]
	v_mfma_f32_16x16x32_bf16 v[72:75], v[202:205], v[222:225], v[72:75]
	v_mfma_f32_16x16x32_bf16 v[100:103], v[182:185], v[230:233], v[100:103]
	v_mfma_f32_16x16x32_bf16 v[68:71], v[202:205], v[230:233], v[68:71]
	v_mfma_f32_16x16x32_bf16 v[96:99], v[182:185], v[238:241], v[96:99]
	v_mfma_f32_16x16x32_bf16 v[64:67], v[202:205], v[238:241], v[64:67]
	v_mfma_f32_16x16x32_bf16 v[108:111], v[186:189], v[218:221], v[108:111]
	v_mfma_f32_16x16x32_bf16 v[76:79], v[206:209], v[218:221], v[76:79]
	v_mfma_f32_16x16x32_bf16 v[104:107], v[186:189], v[226:229], v[104:107]
	v_mfma_f32_16x16x32_bf16 v[72:75], v[206:209], v[226:229], v[72:75]
	v_mfma_f32_16x16x32_bf16 v[100:103], v[186:189], v[234:237], v[100:103]
	v_mfma_f32_16x16x32_bf16 v[68:71], v[206:209], v[234:237], v[68:71]
	v_mfma_f32_16x16x32_bf16 v[96:99], v[186:189], v[242:245], v[96:99]
	v_mfma_f32_16x16x32_bf16 v[64:67], v[206:209], v[242:245], v[64:67]
	s_setprio 0
	s_barrier
	s_add_i32 s10, s16, s63
	s_mov_b32 m0, s10
	ds_read_b128 v[214:217], v199 offset:49152
	ds_read_b128 v[218:221], v199 offset:50176
	ds_read_b128 v[222:225], v199 offset:51200
	ds_read_b128 v[226:229], v199 offset:52224
	ds_read_b128 v[230:233], v199 offset:53248
	ds_read_b128 v[234:237], v199 offset:54272
	ds_read_b128 v[238:241], v199 offset:55296
	ds_read_b128 v[242:245], v199 offset:56320
	global_load_lds_dwordx4 v154, s[98:99]
	s_add_i32 m0, s10, 0x2000
	s_add_u32 s8, s8, 0x80080
	s_addc_u32 s9, s9, 0
	s_add_i32 s10, s17, s63
	global_load_lds_dwordx4 v158, s[98:99]
	s_mov_b32 m0, s10
	s_nop 0
	global_load_lds_dwordx4 v154, s[8:9]
	s_add_i32 m0, s10, 0x2000
	s_nop 0
	global_load_lds_dwordx4 v158, s[8:9]
	s_mov_b32 m0, s82
	s_nop 0
	global_load_lds_dwordx4 v152, s[100:101]
	s_mov_b32 m0, s83
	s_nop 0
	global_load_lds_dwordx4 v156, s[100:101]
	s_waitcnt vmcnt(8)
	s_waitcnt lgkmcnt(0)
	s_setprio 1
	s_barrier
	v_mfma_f32_16x16x32_bf16 v[48:51], v[148:151], v[214:217], v[48:51]
	v_mfma_f32_16x16x32_bf16 v[16:19], v[174:177], v[214:217], v[16:19]
	v_mfma_f32_16x16x32_bf16 v[52:55], v[148:151], v[222:225], v[52:55]
	v_mfma_f32_16x16x32_bf16 v[24:27], v[174:177], v[222:225], v[24:27]
	v_mfma_f32_16x16x32_bf16 v[60:63], v[148:151], v[230:233], v[60:63]
	v_mfma_f32_16x16x32_bf16 v[28:31], v[174:177], v[230:233], v[28:31]
	v_mfma_f32_16x16x32_bf16 v[56:59], v[148:151], v[238:241], v[56:59]
	v_mfma_f32_16x16x32_bf16 v[20:23], v[174:177], v[238:241], v[20:23]
	v_mfma_f32_16x16x32_bf16 v[48:51], v[170:173], v[218:221], v[48:51]
	v_mfma_f32_16x16x32_bf16 v[16:19], v[178:181], v[218:221], v[16:19]
	v_mfma_f32_16x16x32_bf16 v[52:55], v[170:173], v[226:229], v[52:55]
	v_mfma_f32_16x16x32_bf16 v[24:27], v[178:181], v[226:229], v[24:27]
	v_mfma_f32_16x16x32_bf16 v[60:63], v[170:173], v[234:237], v[60:63]
	v_mfma_f32_16x16x32_bf16 v[28:31], v[178:181], v[234:237], v[28:31]
	v_mfma_f32_16x16x32_bf16 v[56:59], v[170:173], v[242:245], v[56:59]
	v_mfma_f32_16x16x32_bf16 v[20:23], v[178:181], v[242:245], v[20:23]
	s_setprio 0
	s_setprio 1
	v_mfma_f32_16x16x32_bf16 v[44:47], v[182:185], v[214:217], v[44:47]
	v_mfma_f32_16x16x32_bf16 v[12:15], v[202:205], v[214:217], v[12:15]
	v_mfma_f32_16x16x32_bf16 v[40:43], v[182:185], v[222:225], v[40:43]
	v_mfma_f32_16x16x32_bf16 v[8:11], v[202:205], v[222:225], v[8:11]
	v_mfma_f32_16x16x32_bf16 v[36:39], v[182:185], v[230:233], v[36:39]
	v_mfma_f32_16x16x32_bf16 v[4:7], v[202:205], v[230:233], v[4:7]
	v_mfma_f32_16x16x32_bf16 v[32:35], v[182:185], v[238:241], v[32:35]
	v_mfma_f32_16x16x32_bf16 v[0:3], v[202:205], v[238:241], v[0:3]
	v_mfma_f32_16x16x32_bf16 v[44:47], v[186:189], v[218:221], v[44:47]
	v_mfma_f32_16x16x32_bf16 v[12:15], v[206:209], v[218:221], v[12:15]
	v_mfma_f32_16x16x32_bf16 v[40:43], v[186:189], v[226:229], v[40:43]
	v_mfma_f32_16x16x32_bf16 v[8:11], v[206:209], v[226:229], v[8:11]
	v_mfma_f32_16x16x32_bf16 v[36:39], v[186:189], v[234:237], v[36:39]
	v_mfma_f32_16x16x32_bf16 v[4:7], v[206:209], v[234:237], v[4:7]
	v_mfma_f32_16x16x32_bf16 v[32:35], v[186:189], v[242:245], v[32:35]
	v_mfma_f32_16x16x32_bf16 v[0:3], v[206:209], v[242:245], v[0:3]
	s_setprio 0
	s_barrier
	s_add_i32 s15, s15, 2
	s_add_u32 s6, s6, 0x100
	s_addc_u32 s7, s7, 0
	s_add_u32 s12, s12, 0x100
	s_addc_u32 s13, s13, 0
	s_cmp_gt_u32 s15, 29
.LBB0_636:
	ds_read_b128 v[148:151], v197
	ds_read_b128 v[170:173], v197 offset:1024
	ds_read_b128 v[174:177], v197 offset:2048
	ds_read_b128 v[178:181], v197 offset:3072
	ds_read_b128 v[182:185], v198
	ds_read_b128 v[186:189], v198 offset:1024
	ds_read_b128 v[202:205], v198 offset:2048
	ds_read_b128 v[206:209], v198 offset:3072
	s_add_u32 s8, s6, 0xfff80080
	s_addc_u32 s9, s7, -1
	s_cmp_eq_u32 s15, 28
	s_cselect_b32 s11, s69, s9
	s_cselect_b32 s10, s68, s8
	s_cselect_b32 s9, s1, s13
	s_cselect_b32 s8, s3, s12
	s_add_i32 m0, s72, 0xc000
	ds_read_b128 v[214:217], v199
	ds_read_b128 v[218:221], v199 offset:1024
	ds_read_b128 v[222:225], v199 offset:2048
	ds_read_b128 v[226:229], v199 offset:3072
	ds_read_b128 v[230:233], v199 offset:4096
	ds_read_b128 v[234:237], v199 offset:5120
	ds_read_b128 v[238:241], v199 offset:6144
	ds_read_b128 v[242:245], v199 offset:7168
	global_load_lds_dwordx4 v162, s[6:7]
	s_add_i32 m0, s72, 0xe000
	s_nop 0
	global_load_lds_dwordx4 v164, s[6:7]
	s_waitcnt vmcnt(8)
	s_waitcnt lgkmcnt(0)
	s_setprio 1
	s_barrier
	v_mfma_f32_16x16x32_bf16 v[112:115], v[148:151], v[214:217], v[112:115]
	v_mfma_f32_16x16x32_bf16 v[80:83], v[174:177], v[214:217], v[80:83]
	v_mfma_f32_16x16x32_bf16 v[116:119], v[148:151], v[222:225], v[116:119]
	v_mfma_f32_16x16x32_bf16 v[88:91], v[174:177], v[222:225], v[88:91]
	v_mfma_f32_16x16x32_bf16 v[124:127], v[148:151], v[230:233], v[124:127]
	v_mfma_f32_16x16x32_bf16 v[92:95], v[174:177], v[230:233], v[92:95]
	v_mfma_f32_16x16x32_bf16 v[120:123], v[148:151], v[238:241], v[120:123]
	v_mfma_f32_16x16x32_bf16 v[84:87], v[174:177], v[238:241], v[84:87]
	v_mfma_f32_16x16x32_bf16 v[112:115], v[170:173], v[218:221], v[112:115]
	v_mfma_f32_16x16x32_bf16 v[80:83], v[178:181], v[218:221], v[80:83]
	v_mfma_f32_16x16x32_bf16 v[116:119], v[170:173], v[226:229], v[116:119]
	v_mfma_f32_16x16x32_bf16 v[88:91], v[178:181], v[226:229], v[88:91]
	v_mfma_f32_16x16x32_bf16 v[124:127], v[170:173], v[234:237], v[124:127]
	v_mfma_f32_16x16x32_bf16 v[92:95], v[178:181], v[234:237], v[92:95]
	v_mfma_f32_16x16x32_bf16 v[120:123], v[170:173], v[242:245], v[120:123]
	v_mfma_f32_16x16x32_bf16 v[84:87], v[178:181], v[242:245], v[84:87]
	s_setprio 0
	s_setprio 1
	v_mfma_f32_16x16x32_bf16 v[108:111], v[182:185], v[214:217], v[108:111]
	v_mfma_f32_16x16x32_bf16 v[76:79], v[202:205], v[214:217], v[76:79]
	v_mfma_f32_16x16x32_bf16 v[104:107], v[182:185], v[222:225], v[104:107]
	v_mfma_f32_16x16x32_bf16 v[72:75], v[202:205], v[222:225], v[72:75]
	v_mfma_f32_16x16x32_bf16 v[100:103], v[182:185], v[230:233], v[100:103]
	v_mfma_f32_16x16x32_bf16 v[68:71], v[202:205], v[230:233], v[68:71]
	v_mfma_f32_16x16x32_bf16 v[96:99], v[182:185], v[238:241], v[96:99]
	v_mfma_f32_16x16x32_bf16 v[64:67], v[202:205], v[238:241], v[64:67]
	v_mfma_f32_16x16x32_bf16 v[108:111], v[186:189], v[218:221], v[108:111]
	v_mfma_f32_16x16x32_bf16 v[76:79], v[206:209], v[218:221], v[76:79]
	v_mfma_f32_16x16x32_bf16 v[104:107], v[186:189], v[226:229], v[104:107]
	v_mfma_f32_16x16x32_bf16 v[72:75], v[206:209], v[226:229], v[72:75]
	v_mfma_f32_16x16x32_bf16 v[100:103], v[186:189], v[234:237], v[100:103]
	v_mfma_f32_16x16x32_bf16 v[68:71], v[206:209], v[234:237], v[68:71]
	v_mfma_f32_16x16x32_bf16 v[96:99], v[186:189], v[242:245], v[96:99]
	v_mfma_f32_16x16x32_bf16 v[64:67], v[206:209], v[242:245], v[64:67]
	s_setprio 0
	s_barrier
	s_add_i32 s16, s94, s63
	s_add_u32 s98, s8, s40
	s_addc_u32 s99, s9, s41
	s_mov_b32 m0, s16
	ds_read_b128 v[214:217], v199 offset:16384
	ds_read_b128 v[218:221], v199 offset:17408
	ds_read_b128 v[222:225], v199 offset:18432
	ds_read_b128 v[226:229], v199 offset:19456
	ds_read_b128 v[230:233], v199 offset:20480
	ds_read_b128 v[234:237], v199 offset:21504
	ds_read_b128 v[238:241], v199 offset:22528
	ds_read_b128 v[242:245], v199 offset:23552
	global_load_lds_dwordx4 v154, s[8:9]
	s_add_i32 m0, s16, 0x2000
	s_add_u32 s16, s8, 0x80000
	s_addc_u32 s17, s9, 0
	s_add_i32 s18, s95, s63
	global_load_lds_dwordx4 v158, s[8:9]
	s_mov_b32 m0, s18
	s_add_u32 s100, s10, s40
	s_addc_u32 s101, s11, s41
	global_load_lds_dwordx4 v154, s[16:17]
	s_add_i32 m0, s18, 0x2000
	s_nop 0
	global_load_lds_dwordx4 v158, s[16:17]
	s_mov_b32 m0, s72
	s_nop 0
	global_load_lds_dwordx4 v152, s[10:11]
	s_mov_b32 m0, s73
	s_nop 0
	global_load_lds_dwordx4 v156, s[10:11]
	s_waitcnt vmcnt(8)
	s_waitcnt lgkmcnt(0)
	s_setprio 1
	s_barrier
	v_mfma_f32_16x16x32_bf16 v[48:51], v[148:151], v[214:217], v[48:51]
	v_mfma_f32_16x16x32_bf16 v[16:19], v[174:177], v[214:217], v[16:19]
	v_mfma_f32_16x16x32_bf16 v[52:55], v[148:151], v[222:225], v[52:55]
	v_mfma_f32_16x16x32_bf16 v[24:27], v[174:177], v[222:225], v[24:27]
	v_mfma_f32_16x16x32_bf16 v[60:63], v[148:151], v[230:233], v[60:63]
	v_mfma_f32_16x16x32_bf16 v[28:31], v[174:177], v[230:233], v[28:31]
	v_mfma_f32_16x16x32_bf16 v[56:59], v[148:151], v[238:241], v[56:59]
	v_mfma_f32_16x16x32_bf16 v[20:23], v[174:177], v[238:241], v[20:23]
	v_mfma_f32_16x16x32_bf16 v[48:51], v[170:173], v[218:221], v[48:51]
	v_mfma_f32_16x16x32_bf16 v[16:19], v[178:181], v[218:221], v[16:19]
	v_mfma_f32_16x16x32_bf16 v[52:55], v[170:173], v[226:229], v[52:55]
	v_mfma_f32_16x16x32_bf16 v[24:27], v[178:181], v[226:229], v[24:27]
	v_mfma_f32_16x16x32_bf16 v[60:63], v[170:173], v[234:237], v[60:63]
	v_mfma_f32_16x16x32_bf16 v[28:31], v[178:181], v[234:237], v[28:31]
	v_mfma_f32_16x16x32_bf16 v[56:59], v[170:173], v[242:245], v[56:59]
	v_mfma_f32_16x16x32_bf16 v[20:23], v[178:181], v[242:245], v[20:23]
	s_setprio 0
	s_setprio 1
	v_mfma_f32_16x16x32_bf16 v[44:47], v[182:185], v[214:217], v[44:47]
	v_mfma_f32_16x16x32_bf16 v[12:15], v[202:205], v[214:217], v[12:15]
	v_mfma_f32_16x16x32_bf16 v[40:43], v[182:185], v[222:225], v[40:43]
	v_mfma_f32_16x16x32_bf16 v[8:11], v[202:205], v[222:225], v[8:11]
	v_mfma_f32_16x16x32_bf16 v[36:39], v[182:185], v[230:233], v[36:39]
	v_mfma_f32_16x16x32_bf16 v[4:7], v[202:205], v[230:233], v[4:7]
	v_mfma_f32_16x16x32_bf16 v[32:35], v[182:185], v[238:241], v[32:35]
	v_mfma_f32_16x16x32_bf16 v[0:3], v[202:205], v[238:241], v[0:3]
	v_mfma_f32_16x16x32_bf16 v[44:47], v[186:189], v[218:221], v[44:47]
	v_mfma_f32_16x16x32_bf16 v[12:15], v[206:209], v[218:221], v[12:15]
	v_mfma_f32_16x16x32_bf16 v[40:43], v[186:189], v[226:229], v[40:43]
	v_mfma_f32_16x16x32_bf16 v[8:11], v[206:209], v[226:229], v[8:11]
	v_mfma_f32_16x16x32_bf16 v[36:39], v[186:189], v[234:237], v[36:39]
	v_mfma_f32_16x16x32_bf16 v[4:7], v[206:209], v[234:237], v[4:7]
	v_mfma_f32_16x16x32_bf16 v[32:35], v[186:189], v[242:245], v[32:35]
	v_mfma_f32_16x16x32_bf16 v[0:3], v[206:209], v[242:245], v[0:3]
	s_setprio 0
	s_barrier
	s_add_i32 s16, 0, 0x18000
	s_add_i32 s17, 0, 0x1c000
	v_add_u32_e32 v178, s16, v196
	v_add_u32_e32 v201, s17, v196
	ds_read_b128 v[148:151], v178
	ds_read_b128 v[170:173], v178 offset:1024
	ds_read_b128 v[174:177], v178 offset:2048
	ds_read_b128 v[178:181], v178 offset:3072
	ds_read_b128 v[182:185], v201
	ds_read_b128 v[186:189], v201 offset:1024
	ds_read_b128 v[202:205], v201 offset:2048
	ds_read_b128 v[206:209], v201 offset:3072
	s_add_u32 s10, s10, 0x80000
	s_addc_u32 s11, s11, 0
	s_mov_b32 m0, s74
	ds_read_b128 v[214:217], v199 offset:32768
	ds_read_b128 v[218:221], v199 offset:33792
	ds_read_b128 v[222:225], v199 offset:34816
	ds_read_b128 v[226:229], v199 offset:35840
	ds_read_b128 v[230:233], v199 offset:36864
	ds_read_b128 v[234:237], v199 offset:37888
	ds_read_b128 v[238:241], v199 offset:38912
	ds_read_b128 v[242:245], v199 offset:39936
	global_load_lds_dwordx4 v152, s[10:11]
	s_mov_b32 m0, s75
	s_nop 0
	global_load_lds_dwordx4 v156, s[10:11]
	s_waitcnt vmcnt(8)
	s_waitcnt lgkmcnt(0)
	s_setprio 1
	s_barrier
	v_mfma_f32_16x16x32_bf16 v[112:115], v[148:151], v[214:217], v[112:115]
	v_mfma_f32_16x16x32_bf16 v[80:83], v[174:177], v[214:217], v[80:83]
	v_mfma_f32_16x16x32_bf16 v[116:119], v[148:151], v[222:225], v[116:119]
	v_mfma_f32_16x16x32_bf16 v[88:91], v[174:177], v[222:225], v[88:91]
	v_mfma_f32_16x16x32_bf16 v[124:127], v[148:151], v[230:233], v[124:127]
	v_mfma_f32_16x16x32_bf16 v[92:95], v[174:177], v[230:233], v[92:95]
	v_mfma_f32_16x16x32_bf16 v[120:123], v[148:151], v[238:241], v[120:123]
	v_mfma_f32_16x16x32_bf16 v[84:87], v[174:177], v[238:241], v[84:87]
	v_mfma_f32_16x16x32_bf16 v[112:115], v[170:173], v[218:221], v[112:115]
	v_mfma_f32_16x16x32_bf16 v[80:83], v[178:181], v[218:221], v[80:83]
	v_mfma_f32_16x16x32_bf16 v[116:119], v[170:173], v[226:229], v[116:119]
	v_mfma_f32_16x16x32_bf16 v[88:91], v[178:181], v[226:229], v[88:91]
	v_mfma_f32_16x16x32_bf16 v[124:127], v[170:173], v[234:237], v[124:127]
	v_mfma_f32_16x16x32_bf16 v[92:95], v[178:181], v[234:237], v[92:95]
	v_mfma_f32_16x16x32_bf16 v[120:123], v[170:173], v[242:245], v[120:123]
	v_mfma_f32_16x16x32_bf16 v[84:87], v[178:181], v[242:245], v[84:87]
	s_setprio 0
	s_setprio 1
	v_mfma_f32_16x16x32_bf16 v[108:111], v[182:185], v[214:217], v[108:111]
	v_mfma_f32_16x16x32_bf16 v[76:79], v[202:205], v[214:217], v[76:79]
	v_mfma_f32_16x16x32_bf16 v[104:107], v[182:185], v[222:225], v[104:107]
	v_mfma_f32_16x16x32_bf16 v[72:75], v[202:205], v[222:225], v[72:75]
	v_mfma_f32_16x16x32_bf16 v[100:103], v[182:185], v[230:233], v[100:103]
	v_mfma_f32_16x16x32_bf16 v[68:71], v[202:205], v[230:233], v[68:71]
	v_mfma_f32_16x16x32_bf16 v[96:99], v[182:185], v[238:241], v[96:99]
	v_mfma_f32_16x16x32_bf16 v[64:67], v[202:205], v[238:241], v[64:67]
	v_mfma_f32_16x16x32_bf16 v[108:111], v[186:189], v[218:221], v[108:111]
	v_mfma_f32_16x16x32_bf16 v[76:79], v[206:209], v[218:221], v[76:79]
	v_mfma_f32_16x16x32_bf16 v[104:107], v[186:189], v[226:229], v[104:107]
	v_mfma_f32_16x16x32_bf16 v[72:75], v[206:209], v[226:229], v[72:75]
	v_mfma_f32_16x16x32_bf16 v[100:103], v[186:189], v[234:237], v[100:103]
	v_mfma_f32_16x16x32_bf16 v[68:71], v[206:209], v[234:237], v[68:71]
	v_mfma_f32_16x16x32_bf16 v[96:99], v[186:189], v[242:245], v[96:99]
	v_mfma_f32_16x16x32_bf16 v[64:67], v[206:209], v[242:245], v[64:67]
	s_setprio 0
	s_barrier
	s_add_i32 s10, s16, s63
	s_mov_b32 m0, s10
	ds_read_b128 v[214:217], v199 offset:49152
	ds_read_b128 v[218:221], v199 offset:50176
	ds_read_b128 v[222:225], v199 offset:51200
	ds_read_b128 v[226:229], v199 offset:52224
	ds_read_b128 v[230:233], v199 offset:53248
	ds_read_b128 v[234:237], v199 offset:54272
	ds_read_b128 v[238:241], v199 offset:55296
	ds_read_b128 v[242:245], v199 offset:56320
	global_load_lds_dwordx4 v154, s[98:99]
	s_add_i32 m0, s10, 0x2000
	s_add_u32 s8, s8, 0x80080
	s_addc_u32 s9, s9, 0
	s_add_i32 s10, s17, s63
	global_load_lds_dwordx4 v158, s[98:99]
	s_mov_b32 m0, s10
	s_nop 0
	global_load_lds_dwordx4 v154, s[8:9]
	s_add_i32 m0, s10, 0x2000
	s_nop 0
	global_load_lds_dwordx4 v158, s[8:9]
	s_mov_b32 m0, s82
	s_nop 0
	global_load_lds_dwordx4 v152, s[100:101]
	s_mov_b32 m0, s83
	s_nop 0
	global_load_lds_dwordx4 v156, s[100:101]
	s_waitcnt vmcnt(8)
	s_waitcnt lgkmcnt(0)
	s_setprio 1
	s_barrier
	v_mfma_f32_16x16x32_bf16 v[48:51], v[148:151], v[214:217], v[48:51]
	v_mfma_f32_16x16x32_bf16 v[16:19], v[174:177], v[214:217], v[16:19]
	v_mfma_f32_16x16x32_bf16 v[52:55], v[148:151], v[222:225], v[52:55]
	v_mfma_f32_16x16x32_bf16 v[24:27], v[174:177], v[222:225], v[24:27]
	v_mfma_f32_16x16x32_bf16 v[60:63], v[148:151], v[230:233], v[60:63]
	v_mfma_f32_16x16x32_bf16 v[28:31], v[174:177], v[230:233], v[28:31]
	v_mfma_f32_16x16x32_bf16 v[56:59], v[148:151], v[238:241], v[56:59]
	v_mfma_f32_16x16x32_bf16 v[20:23], v[174:177], v[238:241], v[20:23]
	v_mfma_f32_16x16x32_bf16 v[48:51], v[170:173], v[218:221], v[48:51]
	v_mfma_f32_16x16x32_bf16 v[16:19], v[178:181], v[218:221], v[16:19]
	v_mfma_f32_16x16x32_bf16 v[52:55], v[170:173], v[226:229], v[52:55]
	v_mfma_f32_16x16x32_bf16 v[24:27], v[178:181], v[226:229], v[24:27]
	v_mfma_f32_16x16x32_bf16 v[60:63], v[170:173], v[234:237], v[60:63]
	v_mfma_f32_16x16x32_bf16 v[28:31], v[178:181], v[234:237], v[28:31]
	v_mfma_f32_16x16x32_bf16 v[56:59], v[170:173], v[242:245], v[56:59]
	v_mfma_f32_16x16x32_bf16 v[20:23], v[178:181], v[242:245], v[20:23]
	s_setprio 0
	s_setprio 1
	v_mfma_f32_16x16x32_bf16 v[44:47], v[182:185], v[214:217], v[44:47]
	v_mfma_f32_16x16x32_bf16 v[12:15], v[202:205], v[214:217], v[12:15]
	v_mfma_f32_16x16x32_bf16 v[40:43], v[182:185], v[222:225], v[40:43]
	v_mfma_f32_16x16x32_bf16 v[8:11], v[202:205], v[222:225], v[8:11]
	v_mfma_f32_16x16x32_bf16 v[36:39], v[182:185], v[230:233], v[36:39]
	v_mfma_f32_16x16x32_bf16 v[4:7], v[202:205], v[230:233], v[4:7]
	v_mfma_f32_16x16x32_bf16 v[32:35], v[182:185], v[238:241], v[32:35]
	v_mfma_f32_16x16x32_bf16 v[0:3], v[202:205], v[238:241], v[0:3]
	v_mfma_f32_16x16x32_bf16 v[44:47], v[186:189], v[218:221], v[44:47]
	v_mfma_f32_16x16x32_bf16 v[12:15], v[206:209], v[218:221], v[12:15]
	v_mfma_f32_16x16x32_bf16 v[40:43], v[186:189], v[226:229], v[40:43]
	v_mfma_f32_16x16x32_bf16 v[8:11], v[206:209], v[226:229], v[8:11]
	v_mfma_f32_16x16x32_bf16 v[36:39], v[186:189], v[234:237], v[36:39]
	v_mfma_f32_16x16x32_bf16 v[4:7], v[206:209], v[234:237], v[4:7]
	v_mfma_f32_16x16x32_bf16 v[32:35], v[186:189], v[242:245], v[32:35]
	v_mfma_f32_16x16x32_bf16 v[0:3], v[206:209], v[242:245], v[0:3]
	s_setprio 0
	s_barrier
	s_add_i32 s15, s15, 2
	s_add_u32 s6, s6, 0x100
	s_addc_u32 s7, s7, 0
	s_add_u32 s12, s12, 0x100
	s_addc_u32 s13, s13, 0
	s_cmp_gt_u32 s15, 29
	s_cbranch_scc0 .LBB0_636
	s_and_b64 vcc, exec, s[42:43]
	s_cbranch_vccz .LBB0_639
	s_barrier

.LBB0_875:
	s_mov_b32 s1, -2
	s_mov_b64 s[4:5], s[22:23]
	ds_read_b128 v[128:131], v188
	ds_read_b128 v[132:135], v188 offset:1024
	ds_read_b128 v[136:139], v188 offset:2048
	ds_read_b128 v[140:143], v188 offset:3072
	ds_read_b128 v[144:147], v189
	ds_read_b128 v[148:151], v189 offset:1024
	ds_read_b128 v[166:169], v189 offset:2048
	ds_read_b128 v[170:173], v189 offset:3072
	s_add_u32 s40, s38, 0x100
	s_addc_u32 s41, s39, 0
	s_cmpk_eq_i32 s1, 0x52
	s_cselect_b32 s45, s37, s41
	s_cselect_b32 s44, s36, s40
	s_cselect_b32 s43, s17, s5
	s_cselect_b32 s42, s16, s4
	s_add_i32 m0, s48, 0xc000
	ds_read_b128 v[174:177], v190
	ds_read_b128 v[178:181], v190 offset:1024
	ds_read_b128 v[194:197], v190 offset:2048
	ds_read_b128 v[198:201], v190 offset:3072
	ds_read_b128 v[202:205], v190 offset:4096
	ds_read_b128 v[206:209], v190 offset:5120
	ds_read_b128 v[210:213], v190 offset:6144
	ds_read_b128 v[214:217], v190 offset:7168
	global_load_lds_dwordx4 v160, s[38:39]
	s_add_i32 m0, s48, 0xe000
	s_nop 0
	global_load_lds_dwordx4 v162, s[38:39]
	s_waitcnt vmcnt(8)
	s_waitcnt lgkmcnt(0)
	s_setprio 1
	s_barrier
	v_mfma_f32_16x16x32_bf16 v[124:127], v[128:131], v[174:177], 0
	v_mfma_f32_16x16x32_bf16 v[120:123], v[136:139], v[174:177], 0
	v_mfma_f32_16x16x32_bf16 v[108:111], v[128:131], v[194:197], 0
	v_mfma_f32_16x16x32_bf16 v[104:107], v[136:139], v[194:197], 0
	v_mfma_f32_16x16x32_bf16 v[92:95], v[128:131], v[202:205], 0
	v_mfma_f32_16x16x32_bf16 v[88:91], v[136:139], v[202:205], 0
	v_mfma_f32_16x16x32_bf16 v[76:79], v[128:131], v[210:213], 0
	v_mfma_f32_16x16x32_bf16 v[72:75], v[136:139], v[210:213], 0
	v_mfma_f32_16x16x32_bf16 v[124:127], v[132:135], v[178:181], v[124:127]
	v_mfma_f32_16x16x32_bf16 v[120:123], v[140:143], v[178:181], v[120:123]
	v_mfma_f32_16x16x32_bf16 v[108:111], v[132:135], v[198:201], v[108:111]
	v_mfma_f32_16x16x32_bf16 v[104:107], v[140:143], v[198:201], v[104:107]
	v_mfma_f32_16x16x32_bf16 v[92:95], v[132:135], v[206:209], v[92:95]
	v_mfma_f32_16x16x32_bf16 v[88:91], v[140:143], v[206:209], v[88:91]
	v_mfma_f32_16x16x32_bf16 v[76:79], v[132:135], v[214:217], v[76:79]
	v_mfma_f32_16x16x32_bf16 v[72:75], v[140:143], v[214:217], v[72:75]
	s_setprio 0
	s_setprio 1
	v_mfma_f32_16x16x32_bf16 v[116:119], v[144:147], v[174:177], 0
	v_mfma_f32_16x16x32_bf16 v[112:115], v[166:169], v[174:177], 0
	v_mfma_f32_16x16x32_bf16 v[100:103], v[144:147], v[194:197], 0
	v_mfma_f32_16x16x32_bf16 v[96:99], v[166:169], v[194:197], 0
	v_mfma_f32_16x16x32_bf16 v[84:87], v[144:147], v[202:205], 0
	v_mfma_f32_16x16x32_bf16 v[80:83], v[166:169], v[202:205], 0
	v_mfma_f32_16x16x32_bf16 v[68:71], v[144:147], v[210:213], 0
	v_mfma_f32_16x16x32_bf16 v[64:67], v[166:169], v[210:213], 0
	v_mfma_f32_16x16x32_bf16 v[116:119], v[148:151], v[178:181], v[116:119]
	v_mfma_f32_16x16x32_bf16 v[112:115], v[170:173], v[178:181], v[112:115]
	v_mfma_f32_16x16x32_bf16 v[100:103], v[148:151], v[198:201], v[100:103]
	v_mfma_f32_16x16x32_bf16 v[96:99], v[170:173], v[198:201], v[96:99]
	v_mfma_f32_16x16x32_bf16 v[84:87], v[148:151], v[206:209], v[84:87]
	v_mfma_f32_16x16x32_bf16 v[80:83], v[170:173], v[206:209], v[80:83]
	v_mfma_f32_16x16x32_bf16 v[68:71], v[148:151], v[214:217], v[68:71]
	v_mfma_f32_16x16x32_bf16 v[64:67], v[170:173], v[214:217], v[64:67]
	s_setprio 0
	s_barrier
	s_add_i32 s3, s70, s33
	s_add_u32 s98, s42, s24
	s_addc_u32 s99, s43, s25
	s_mov_b32 m0, s3
	ds_read_b128 v[174:177], v190 offset:16384
	ds_read_b128 v[178:181], v190 offset:17408
	ds_read_b128 v[194:197], v190 offset:18432
	ds_read_b128 v[198:201], v190 offset:19456
	ds_read_b128 v[202:205], v190 offset:20480
	ds_read_b128 v[206:209], v190 offset:21504
	ds_read_b128 v[210:213], v190 offset:22528
	ds_read_b128 v[214:217], v190 offset:23552
	global_load_lds_dwordx4 v154, s[42:43]
	s_add_i32 m0, s3, 0x2000
	s_add_u32 s38, s42, 0x158000
	s_addc_u32 s39, s43, 0
	s_add_i32 s3, s71, s33
	global_load_lds_dwordx4 v158, s[42:43]
	s_mov_b32 m0, s3
	s_add_u32 s100, s44, s24
	s_addc_u32 s101, s45, s25
	global_load_lds_dwordx4 v154, s[38:39]
	s_add_i32 m0, s3, 0x2000
	s_nop 0
	global_load_lds_dwordx4 v158, s[38:39]
	s_mov_b32 m0, s48
	s_nop 0
	global_load_lds_dwordx4 v152, s[44:45]
	s_mov_b32 m0, s49
	s_nop 0
	global_load_lds_dwordx4 v156, s[44:45]
	s_waitcnt vmcnt(8)
	s_waitcnt lgkmcnt(0)
	s_setprio 1
	s_barrier
	v_mfma_f32_16x16x32_bf16 v[60:63], v[128:131], v[174:177], 0
	v_mfma_f32_16x16x32_bf16 v[56:59], v[136:139], v[174:177], 0
	v_mfma_f32_16x16x32_bf16 v[44:47], v[128:131], v[194:197], 0
	v_mfma_f32_16x16x32_bf16 v[40:43], v[136:139], v[194:197], 0
	v_mfma_f32_16x16x32_bf16 v[28:31], v[128:131], v[202:205], 0
	v_mfma_f32_16x16x32_bf16 v[24:27], v[136:139], v[202:205], 0
	v_mfma_f32_16x16x32_bf16 v[12:15], v[128:131], v[210:213], 0
	v_mfma_f32_16x16x32_bf16 v[8:11], v[136:139], v[210:213], 0
	v_mfma_f32_16x16x32_bf16 v[60:63], v[132:135], v[178:181], v[60:63]
	v_mfma_f32_16x16x32_bf16 v[56:59], v[140:143], v[178:181], v[56:59]
	v_mfma_f32_16x16x32_bf16 v[44:47], v[132:135], v[198:201], v[44:47]
	v_mfma_f32_16x16x32_bf16 v[40:43], v[140:143], v[198:201], v[40:43]
	v_mfma_f32_16x16x32_bf16 v[28:31], v[132:135], v[206:209], v[28:31]
	v_mfma_f32_16x16x32_bf16 v[24:27], v[140:143], v[206:209], v[24:27]
	v_mfma_f32_16x16x32_bf16 v[12:15], v[132:135], v[214:217], v[12:15]
	v_mfma_f32_16x16x32_bf16 v[8:11], v[140:143], v[214:217], v[8:11]
	s_setprio 0
	s_setprio 1
	v_mfma_f32_16x16x32_bf16 v[52:55], v[144:147], v[174:177], 0
	v_mfma_f32_16x16x32_bf16 v[48:51], v[166:169], v[174:177], 0
	v_mfma_f32_16x16x32_bf16 v[36:39], v[144:147], v[194:197], 0
	v_mfma_f32_16x16x32_bf16 v[32:35], v[166:169], v[194:197], 0
	v_mfma_f32_16x16x32_bf16 v[20:23], v[144:147], v[202:205], 0
	v_mfma_f32_16x16x32_bf16 v[16:19], v[166:169], v[202:205], 0
	v_mfma_f32_16x16x32_bf16 v[4:7], v[144:147], v[210:213], 0
	v_mfma_f32_16x16x32_bf16 v[0:3], v[166:169], v[210:213], 0
	v_mfma_f32_16x16x32_bf16 v[52:55], v[148:151], v[178:181], v[52:55]
	v_mfma_f32_16x16x32_bf16 v[48:51], v[170:173], v[178:181], v[48:51]
	v_mfma_f32_16x16x32_bf16 v[36:39], v[148:151], v[198:201], v[36:39]
	v_mfma_f32_16x16x32_bf16 v[32:35], v[170:173], v[198:201], v[32:35]
	v_mfma_f32_16x16x32_bf16 v[20:23], v[148:151], v[206:209], v[20:23]
	v_mfma_f32_16x16x32_bf16 v[16:19], v[170:173], v[206:209], v[16:19]
	v_mfma_f32_16x16x32_bf16 v[4:7], v[148:151], v[214:217], v[4:7]
	v_mfma_f32_16x16x32_bf16 v[0:3], v[170:173], v[214:217], v[0:3]
	s_setprio 0
	s_barrier
	s_add_i32 s3, 0, 0x18000
	s_add_i32 s73, 0, 0x1c000
	v_add_u32_e32 v140, s3, v187
	v_add_u32_e32 v170, s73, v187
	ds_read_b128 v[128:131], v140
	ds_read_b128 v[132:135], v140 offset:1024
	ds_read_b128 v[136:139], v140 offset:2048
	ds_read_b128 v[140:143], v140 offset:3072
	ds_read_b128 v[144:147], v170
	ds_read_b128 v[148:151], v170 offset:1024
	ds_read_b128 v[166:169], v170 offset:2048
	ds_read_b128 v[170:173], v170 offset:3072
	s_add_u32 s38, s44, 0x158000
	s_addc_u32 s39, s45, 0
	s_mov_b32 m0, s51
	ds_read_b128 v[174:177], v190 offset:32768
	ds_read_b128 v[178:181], v190 offset:33792
	ds_read_b128 v[194:197], v190 offset:34816
	ds_read_b128 v[198:201], v190 offset:35840
	ds_read_b128 v[202:205], v190 offset:36864
	ds_read_b128 v[206:209], v190 offset:37888
	ds_read_b128 v[210:213], v190 offset:38912
	ds_read_b128 v[214:217], v190 offset:39936
	global_load_lds_dwordx4 v152, s[38:39]
	s_mov_b32 m0, s52
	s_nop 0
	global_load_lds_dwordx4 v156, s[38:39]
	s_waitcnt vmcnt(8)
	s_waitcnt lgkmcnt(0)
	s_setprio 1
	s_barrier
	v_mfma_f32_16x16x32_bf16 v[124:127], v[128:131], v[174:177], v[124:127]
	v_mfma_f32_16x16x32_bf16 v[120:123], v[136:139], v[174:177], v[120:123]
	v_mfma_f32_16x16x32_bf16 v[108:111], v[128:131], v[194:197], v[108:111]
	v_mfma_f32_16x16x32_bf16 v[104:107], v[136:139], v[194:197], v[104:107]
	v_mfma_f32_16x16x32_bf16 v[92:95], v[128:131], v[202:205], v[92:95]
	v_mfma_f32_16x16x32_bf16 v[88:91], v[136:139], v[202:205], v[88:91]
	v_mfma_f32_16x16x32_bf16 v[76:79], v[128:131], v[210:213], v[76:79]
	v_mfma_f32_16x16x32_bf16 v[72:75], v[136:139], v[210:213], v[72:75]
	v_mfma_f32_16x16x32_bf16 v[124:127], v[132:135], v[178:181], v[124:127]
	v_mfma_f32_16x16x32_bf16 v[120:123], v[140:143], v[178:181], v[120:123]
	v_mfma_f32_16x16x32_bf16 v[108:111], v[132:135], v[198:201], v[108:111]
	v_mfma_f32_16x16x32_bf16 v[104:107], v[140:143], v[198:201], v[104:107]
	v_mfma_f32_16x16x32_bf16 v[92:95], v[132:135], v[206:209], v[92:95]
	v_mfma_f32_16x16x32_bf16 v[88:91], v[140:143], v[206:209], v[88:91]
	v_mfma_f32_16x16x32_bf16 v[76:79], v[132:135], v[214:217], v[76:79]
	v_mfma_f32_16x16x32_bf16 v[72:75], v[140:143], v[214:217], v[72:75]
	s_setprio 0
	s_setprio 1
	v_mfma_f32_16x16x32_bf16 v[116:119], v[144:147], v[174:177], v[116:119]
	v_mfma_f32_16x16x32_bf16 v[112:115], v[166:169], v[174:177], v[112:115]
	v_mfma_f32_16x16x32_bf16 v[100:103], v[144:147], v[194:197], v[100:103]
	v_mfma_f32_16x16x32_bf16 v[96:99], v[166:169], v[194:197], v[96:99]
	v_mfma_f32_16x16x32_bf16 v[84:87], v[144:147], v[202:205], v[84:87]
	v_mfma_f32_16x16x32_bf16 v[80:83], v[166:169], v[202:205], v[80:83]
	v_mfma_f32_16x16x32_bf16 v[68:71], v[144:147], v[210:213], v[68:71]
	v_mfma_f32_16x16x32_bf16 v[64:67], v[166:169], v[210:213], v[64:67]
	v_mfma_f32_16x16x32_bf16 v[116:119], v[148:151], v[178:181], v[116:119]
	v_mfma_f32_16x16x32_bf16 v[112:115], v[170:173], v[178:181], v[112:115]
	v_mfma_f32_16x16x32_bf16 v[100:103], v[148:151], v[198:201], v[100:103]
	v_mfma_f32_16x16x32_bf16 v[96:99], v[170:173], v[198:201], v[96:99]
	v_mfma_f32_16x16x32_bf16 v[84:87], v[148:151], v[206:209], v[84:87]
	v_mfma_f32_16x16x32_bf16 v[80:83], v[170:173], v[206:209], v[80:83]
	v_mfma_f32_16x16x32_bf16 v[68:71], v[148:151], v[214:217], v[68:71]
	v_mfma_f32_16x16x32_bf16 v[64:67], v[170:173], v[214:217], v[64:67]
	s_setprio 0
	s_barrier
	s_add_i32 s3, s3, s33
	s_mov_b32 m0, s3
	ds_read_b128 v[174:177], v190 offset:49152
	ds_read_b128 v[178:181], v190 offset:50176
	ds_read_b128 v[194:197], v190 offset:51200
	ds_read_b128 v[198:201], v190 offset:52224
	ds_read_b128 v[202:205], v190 offset:53248
	ds_read_b128 v[206:209], v190 offset:54272
	ds_read_b128 v[210:213], v190 offset:55296
	ds_read_b128 v[214:217], v190 offset:56320
	global_load_lds_dwordx4 v154, s[98:99]
	s_add_i32 m0, s3, 0x2000
	s_add_u32 s38, s42, 0x158080
	s_addc_u32 s39, s43, 0
	s_add_i32 s3, s73, s33
	global_load_lds_dwordx4 v158, s[98:99]
	s_mov_b32 m0, s3
	s_nop 0
	global_load_lds_dwordx4 v154, s[38:39]
	s_add_i32 m0, s3, 0x2000
	s_nop 0
	global_load_lds_dwordx4 v158, s[38:39]
	s_mov_b32 m0, s56
	s_nop 0
	global_load_lds_dwordx4 v152, s[100:101]
	s_mov_b32 m0, s57
	s_nop 0
	global_load_lds_dwordx4 v156, s[100:101]
	s_waitcnt vmcnt(8)
	s_waitcnt lgkmcnt(0)
	s_setprio 1
	s_barrier
	v_mfma_f32_16x16x32_bf16 v[60:63], v[128:131], v[174:177], v[60:63]
	v_mfma_f32_16x16x32_bf16 v[56:59], v[136:139], v[174:177], v[56:59]
	v_mfma_f32_16x16x32_bf16 v[44:47], v[128:131], v[194:197], v[44:47]
	v_mfma_f32_16x16x32_bf16 v[40:43], v[136:139], v[194:197], v[40:43]
	v_mfma_f32_16x16x32_bf16 v[28:31], v[128:131], v[202:205], v[28:31]
	v_mfma_f32_16x16x32_bf16 v[24:27], v[136:139], v[202:205], v[24:27]
	v_mfma_f32_16x16x32_bf16 v[12:15], v[128:131], v[210:213], v[12:15]
	v_mfma_f32_16x16x32_bf16 v[8:11], v[136:139], v[210:213], v[8:11]
	v_mfma_f32_16x16x32_bf16 v[60:63], v[132:135], v[178:181], v[60:63]
	v_mfma_f32_16x16x32_bf16 v[56:59], v[140:143], v[178:181], v[56:59]
	v_mfma_f32_16x16x32_bf16 v[44:47], v[132:135], v[198:201], v[44:47]
	v_mfma_f32_16x16x32_bf16 v[40:43], v[140:143], v[198:201], v[40:43]
	v_mfma_f32_16x16x32_bf16 v[28:31], v[132:135], v[206:209], v[28:31]
	v_mfma_f32_16x16x32_bf16 v[24:27], v[140:143], v[206:209], v[24:27]
	v_mfma_f32_16x16x32_bf16 v[12:15], v[132:135], v[214:217], v[12:15]
	v_mfma_f32_16x16x32_bf16 v[8:11], v[140:143], v[214:217], v[8:11]
	s_setprio 0
	s_setprio 1
	v_mfma_f32_16x16x32_bf16 v[52:55], v[144:147], v[174:177], v[52:55]
	v_mfma_f32_16x16x32_bf16 v[48:51], v[166:169], v[174:177], v[48:51]
	v_mfma_f32_16x16x32_bf16 v[36:39], v[144:147], v[194:197], v[36:39]
	v_mfma_f32_16x16x32_bf16 v[32:35], v[166:169], v[194:197], v[32:35]
	v_mfma_f32_16x16x32_bf16 v[20:23], v[144:147], v[202:205], v[20:23]
	v_mfma_f32_16x16x32_bf16 v[16:19], v[166:169], v[202:205], v[16:19]
	v_mfma_f32_16x16x32_bf16 v[4:7], v[144:147], v[210:213], v[4:7]
	v_mfma_f32_16x16x32_bf16 v[0:3], v[166:169], v[210:213], v[0:3]
	v_mfma_f32_16x16x32_bf16 v[52:55], v[148:151], v[178:181], v[52:55]
	v_mfma_f32_16x16x32_bf16 v[48:51], v[170:173], v[178:181], v[48:51]
	v_mfma_f32_16x16x32_bf16 v[36:39], v[148:151], v[198:201], v[36:39]
	v_mfma_f32_16x16x32_bf16 v[32:35], v[170:173], v[198:201], v[32:35]
	v_mfma_f32_16x16x32_bf16 v[20:23], v[148:151], v[206:209], v[20:23]
	v_mfma_f32_16x16x32_bf16 v[16:19], v[170:173], v[206:209], v[16:19]
	v_mfma_f32_16x16x32_bf16 v[4:7], v[148:151], v[214:217], v[4:7]
	v_mfma_f32_16x16x32_bf16 v[0:3], v[170:173], v[214:217], v[0:3]
	s_setprio 0
	s_barrier
	s_add_i32 s1, s1, 2
	s_add_u32 s4, s4, 0x100
	s_addc_u32 s5, s5, 0
	s_cmpk_gt_u32 s1, 0x53
	s_mov_b64 s[38:39], s[40:41]
.LBB0_876:
	ds_read_b128 v[128:131], v188
	ds_read_b128 v[132:135], v188 offset:1024
	ds_read_b128 v[136:139], v188 offset:2048
	ds_read_b128 v[140:143], v188 offset:3072
	ds_read_b128 v[144:147], v189
	ds_read_b128 v[148:151], v189 offset:1024
	ds_read_b128 v[166:169], v189 offset:2048
	ds_read_b128 v[170:173], v189 offset:3072
	s_add_u32 s40, s38, 0x100
	s_addc_u32 s41, s39, 0
	s_cmpk_eq_i32 s1, 0x52
	s_cselect_b32 s45, s37, s41
	s_cselect_b32 s44, s36, s40
	s_cselect_b32 s43, s17, s5
	s_cselect_b32 s42, s16, s4
	s_add_i32 m0, s48, 0xc000
	ds_read_b128 v[174:177], v190
	ds_read_b128 v[178:181], v190 offset:1024
	ds_read_b128 v[194:197], v190 offset:2048
	ds_read_b128 v[198:201], v190 offset:3072
	ds_read_b128 v[202:205], v190 offset:4096
	ds_read_b128 v[206:209], v190 offset:5120
	ds_read_b128 v[210:213], v190 offset:6144
	ds_read_b128 v[214:217], v190 offset:7168
	global_load_lds_dwordx4 v160, s[38:39]
	s_add_i32 m0, s48, 0xe000
	s_nop 0
	global_load_lds_dwordx4 v162, s[38:39]
	s_waitcnt vmcnt(8)
	s_waitcnt lgkmcnt(0)
	s_setprio 1
	s_barrier
	v_mfma_f32_16x16x32_bf16 v[124:127], v[128:131], v[174:177], v[124:127]
	v_mfma_f32_16x16x32_bf16 v[120:123], v[136:139], v[174:177], v[120:123]
	v_mfma_f32_16x16x32_bf16 v[108:111], v[128:131], v[194:197], v[108:111]
	v_mfma_f32_16x16x32_bf16 v[104:107], v[136:139], v[194:197], v[104:107]
	v_mfma_f32_16x16x32_bf16 v[92:95], v[128:131], v[202:205], v[92:95]
	v_mfma_f32_16x16x32_bf16 v[88:91], v[136:139], v[202:205], v[88:91]
	v_mfma_f32_16x16x32_bf16 v[76:79], v[128:131], v[210:213], v[76:79]
	v_mfma_f32_16x16x32_bf16 v[72:75], v[136:139], v[210:213], v[72:75]
	v_mfma_f32_16x16x32_bf16 v[124:127], v[132:135], v[178:181], v[124:127]
	v_mfma_f32_16x16x32_bf16 v[120:123], v[140:143], v[178:181], v[120:123]
	v_mfma_f32_16x16x32_bf16 v[108:111], v[132:135], v[198:201], v[108:111]
	v_mfma_f32_16x16x32_bf16 v[104:107], v[140:143], v[198:201], v[104:107]
	v_mfma_f32_16x16x32_bf16 v[92:95], v[132:135], v[206:209], v[92:95]
	v_mfma_f32_16x16x32_bf16 v[88:91], v[140:143], v[206:209], v[88:91]
	v_mfma_f32_16x16x32_bf16 v[76:79], v[132:135], v[214:217], v[76:79]
	v_mfma_f32_16x16x32_bf16 v[72:75], v[140:143], v[214:217], v[72:75]
	s_setprio 0
	s_setprio 1
	v_mfma_f32_16x16x32_bf16 v[116:119], v[144:147], v[174:177], v[116:119]
	v_mfma_f32_16x16x32_bf16 v[112:115], v[166:169], v[174:177], v[112:115]
	v_mfma_f32_16x16x32_bf16 v[100:103], v[144:147], v[194:197], v[100:103]
	v_mfma_f32_16x16x32_bf16 v[96:99], v[166:169], v[194:197], v[96:99]
	v_mfma_f32_16x16x32_bf16 v[84:87], v[144:147], v[202:205], v[84:87]
	v_mfma_f32_16x16x32_bf16 v[80:83], v[166:169], v[202:205], v[80:83]
	v_mfma_f32_16x16x32_bf16 v[68:71], v[144:147], v[210:213], v[68:71]
	v_mfma_f32_16x16x32_bf16 v[64:67], v[166:169], v[210:213], v[64:67]
	v_mfma_f32_16x16x32_bf16 v[116:119], v[148:151], v[178:181], v[116:119]
	v_mfma_f32_16x16x32_bf16 v[112:115], v[170:173], v[178:181], v[112:115]
	v_mfma_f32_16x16x32_bf16 v[100:103], v[148:151], v[198:201], v[100:103]
	v_mfma_f32_16x16x32_bf16 v[96:99], v[170:173], v[198:201], v[96:99]
	v_mfma_f32_16x16x32_bf16 v[84:87], v[148:151], v[206:209], v[84:87]
	v_mfma_f32_16x16x32_bf16 v[80:83], v[170:173], v[206:209], v[80:83]
	v_mfma_f32_16x16x32_bf16 v[68:71], v[148:151], v[214:217], v[68:71]
	v_mfma_f32_16x16x32_bf16 v[64:67], v[170:173], v[214:217], v[64:67]
	s_setprio 0
	s_barrier
	s_add_i32 s3, s70, s33
	s_add_u32 s98, s42, s24
	s_addc_u32 s99, s43, s25
	s_mov_b32 m0, s3
	ds_read_b128 v[174:177], v190 offset:16384
	ds_read_b128 v[178:181], v190 offset:17408
	ds_read_b128 v[194:197], v190 offset:18432
	ds_read_b128 v[198:201], v190 offset:19456
	ds_read_b128 v[202:205], v190 offset:20480
	ds_read_b128 v[206:209], v190 offset:21504
	ds_read_b128 v[210:213], v190 offset:22528
	ds_read_b128 v[214:217], v190 offset:23552
	global_load_lds_dwordx4 v154, s[42:43]
	s_add_i32 m0, s3, 0x2000
	s_add_u32 s38, s42, 0x158000
	s_addc_u32 s39, s43, 0
	s_add_i32 s3, s71, s33
	global_load_lds_dwordx4 v158, s[42:43]
	s_mov_b32 m0, s3
	s_add_u32 s100, s44, s24
	s_addc_u32 s101, s45, s25
	global_load_lds_dwordx4 v154, s[38:39]
	s_add_i32 m0, s3, 0x2000
	s_nop 0
	global_load_lds_dwordx4 v158, s[38:39]
	s_mov_b32 m0, s48
	s_nop 0
	global_load_lds_dwordx4 v152, s[44:45]
	s_mov_b32 m0, s49
	s_nop 0
	global_load_lds_dwordx4 v156, s[44:45]
	s_waitcnt vmcnt(8)
	s_waitcnt lgkmcnt(0)
	s_setprio 1
	s_barrier
	v_mfma_f32_16x16x32_bf16 v[60:63], v[128:131], v[174:177], v[60:63]
	v_mfma_f32_16x16x32_bf16 v[56:59], v[136:139], v[174:177], v[56:59]
	v_mfma_f32_16x16x32_bf16 v[44:47], v[128:131], v[194:197], v[44:47]
	v_mfma_f32_16x16x32_bf16 v[40:43], v[136:139], v[194:197], v[40:43]
	v_mfma_f32_16x16x32_bf16 v[28:31], v[128:131], v[202:205], v[28:31]
	v_mfma_f32_16x16x32_bf16 v[24:27], v[136:139], v[202:205], v[24:27]
	v_mfma_f32_16x16x32_bf16 v[12:15], v[128:131], v[210:213], v[12:15]
	v_mfma_f32_16x16x32_bf16 v[8:11], v[136:139], v[210:213], v[8:11]
	v_mfma_f32_16x16x32_bf16 v[60:63], v[132:135], v[178:181], v[60:63]
	v_mfma_f32_16x16x32_bf16 v[56:59], v[140:143], v[178:181], v[56:59]
	v_mfma_f32_16x16x32_bf16 v[44:47], v[132:135], v[198:201], v[44:47]
	v_mfma_f32_16x16x32_bf16 v[40:43], v[140:143], v[198:201], v[40:43]
	v_mfma_f32_16x16x32_bf16 v[28:31], v[132:135], v[206:209], v[28:31]
	v_mfma_f32_16x16x32_bf16 v[24:27], v[140:143], v[206:209], v[24:27]
	v_mfma_f32_16x16x32_bf16 v[12:15], v[132:135], v[214:217], v[12:15]
	v_mfma_f32_16x16x32_bf16 v[8:11], v[140:143], v[214:217], v[8:11]
	s_setprio 0
	s_setprio 1
	v_mfma_f32_16x16x32_bf16 v[52:55], v[144:147], v[174:177], v[52:55]
	v_mfma_f32_16x16x32_bf16 v[48:51], v[166:169], v[174:177], v[48:51]
	v_mfma_f32_16x16x32_bf16 v[36:39], v[144:147], v[194:197], v[36:39]
	v_mfma_f32_16x16x32_bf16 v[32:35], v[166:169], v[194:197], v[32:35]
	v_mfma_f32_16x16x32_bf16 v[20:23], v[144:147], v[202:205], v[20:23]
	v_mfma_f32_16x16x32_bf16 v[16:19], v[166:169], v[202:205], v[16:19]
	v_mfma_f32_16x16x32_bf16 v[4:7], v[144:147], v[210:213], v[4:7]
	v_mfma_f32_16x16x32_bf16 v[0:3], v[166:169], v[210:213], v[0:3]
	v_mfma_f32_16x16x32_bf16 v[52:55], v[148:151], v[178:181], v[52:55]
	v_mfma_f32_16x16x32_bf16 v[48:51], v[170:173], v[178:181], v[48:51]
	v_mfma_f32_16x16x32_bf16 v[36:39], v[148:151], v[198:201], v[36:39]
	v_mfma_f32_16x16x32_bf16 v[32:35], v[170:173], v[198:201], v[32:35]
	v_mfma_f32_16x16x32_bf16 v[20:23], v[148:151], v[206:209], v[20:23]
	v_mfma_f32_16x16x32_bf16 v[16:19], v[170:173], v[206:209], v[16:19]
	v_mfma_f32_16x16x32_bf16 v[4:7], v[148:151], v[214:217], v[4:7]
	v_mfma_f32_16x16x32_bf16 v[0:3], v[170:173], v[214:217], v[0:3]
	s_setprio 0
	s_barrier
	s_add_i32 s3, 0, 0x18000
	s_add_i32 s73, 0, 0x1c000
	v_add_u32_e32 v140, s3, v187
	v_add_u32_e32 v170, s73, v187
	ds_read_b128 v[128:131], v140
	ds_read_b128 v[132:135], v140 offset:1024
	ds_read_b128 v[136:139], v140 offset:2048
	ds_read_b128 v[140:143], v140 offset:3072
	ds_read_b128 v[144:147], v170
	ds_read_b128 v[148:151], v170 offset:1024
	ds_read_b128 v[166:169], v170 offset:2048
	ds_read_b128 v[170:173], v170 offset:3072
	s_add_u32 s38, s44, 0x158000
	s_addc_u32 s39, s45, 0
	s_mov_b32 m0, s51
	ds_read_b128 v[174:177], v190 offset:32768
	ds_read_b128 v[178:181], v190 offset:33792
	ds_read_b128 v[194:197], v190 offset:34816
	ds_read_b128 v[198:201], v190 offset:35840
	ds_read_b128 v[202:205], v190 offset:36864
	ds_read_b128 v[206:209], v190 offset:37888
	ds_read_b128 v[210:213], v190 offset:38912
	ds_read_b128 v[214:217], v190 offset:39936
	global_load_lds_dwordx4 v152, s[38:39]
	s_mov_b32 m0, s52
	s_nop 0
	global_load_lds_dwordx4 v156, s[38:39]
	s_waitcnt vmcnt(8)
	s_waitcnt lgkmcnt(0)
	s_setprio 1
	s_barrier
	v_mfma_f32_16x16x32_bf16 v[124:127], v[128:131], v[174:177], v[124:127]
	v_mfma_f32_16x16x32_bf16 v[120:123], v[136:139], v[174:177], v[120:123]
	v_mfma_f32_16x16x32_bf16 v[108:111], v[128:131], v[194:197], v[108:111]
	v_mfma_f32_16x16x32_bf16 v[104:107], v[136:139], v[194:197], v[104:107]
	v_mfma_f32_16x16x32_bf16 v[92:95], v[128:131], v[202:205], v[92:95]
	v_mfma_f32_16x16x32_bf16 v[88:91], v[136:139], v[202:205], v[88:91]
	v_mfma_f32_16x16x32_bf16 v[76:79], v[128:131], v[210:213], v[76:79]
	v_mfma_f32_16x16x32_bf16 v[72:75], v[136:139], v[210:213], v[72:75]
	v_mfma_f32_16x16x32_bf16 v[124:127], v[132:135], v[178:181], v[124:127]
	v_mfma_f32_16x16x32_bf16 v[120:123], v[140:143], v[178:181], v[120:123]
	v_mfma_f32_16x16x32_bf16 v[108:111], v[132:135], v[198:201], v[108:111]
	v_mfma_f32_16x16x32_bf16 v[104:107], v[140:143], v[198:201], v[104:107]
	v_mfma_f32_16x16x32_bf16 v[92:95], v[132:135], v[206:209], v[92:95]
	v_mfma_f32_16x16x32_bf16 v[88:91], v[140:143], v[206:209], v[88:91]
	v_mfma_f32_16x16x32_bf16 v[76:79], v[132:135], v[214:217], v[76:79]
	v_mfma_f32_16x16x32_bf16 v[72:75], v[140:143], v[214:217], v[72:75]
	s_setprio 0
	s_setprio 1
	v_mfma_f32_16x16x32_bf16 v[116:119], v[144:147], v[174:177], v[116:119]
	v_mfma_f32_16x16x32_bf16 v[112:115], v[166:169], v[174:177], v[112:115]
	v_mfma_f32_16x16x32_bf16 v[100:103], v[144:147], v[194:197], v[100:103]
	v_mfma_f32_16x16x32_bf16 v[96:99], v[166:169], v[194:197], v[96:99]
	v_mfma_f32_16x16x32_bf16 v[84:87], v[144:147], v[202:205], v[84:87]
	v_mfma_f32_16x16x32_bf16 v[80:83], v[166:169], v[202:205], v[80:83]
	v_mfma_f32_16x16x32_bf16 v[68:71], v[144:147], v[210:213], v[68:71]
	v_mfma_f32_16x16x32_bf16 v[64:67], v[166:169], v[210:213], v[64:67]
	v_mfma_f32_16x16x32_bf16 v[116:119], v[148:151], v[178:181], v[116:119]
	v_mfma_f32_16x16x32_bf16 v[112:115], v[170:173], v[178:181], v[112:115]
	v_mfma_f32_16x16x32_bf16 v[100:103], v[148:151], v[198:201], v[100:103]
	v_mfma_f32_16x16x32_bf16 v[96:99], v[170:173], v[198:201], v[96:99]
	v_mfma_f32_16x16x32_bf16 v[84:87], v[148:151], v[206:209], v[84:87]
	v_mfma_f32_16x16x32_bf16 v[80:83], v[170:173], v[206:209], v[80:83]
	v_mfma_f32_16x16x32_bf16 v[68:71], v[148:151], v[214:217], v[68:71]
	v_mfma_f32_16x16x32_bf16 v[64:67], v[170:173], v[214:217], v[64:67]
	s_setprio 0
	s_barrier
	s_add_i32 s3, s3, s33
	s_mov_b32 m0, s3
	ds_read_b128 v[174:177], v190 offset:49152
	ds_read_b128 v[178:181], v190 offset:50176
	ds_read_b128 v[194:197], v190 offset:51200
	ds_read_b128 v[198:201], v190 offset:52224
	ds_read_b128 v[202:205], v190 offset:53248
	ds_read_b128 v[206:209], v190 offset:54272
	ds_read_b128 v[210:213], v190 offset:55296
	ds_read_b128 v[214:217], v190 offset:56320
	global_load_lds_dwordx4 v154, s[98:99]
	s_add_i32 m0, s3, 0x2000
	s_add_u32 s38, s42, 0x158080
	s_addc_u32 s39, s43, 0
	s_add_i32 s3, s73, s33
	global_load_lds_dwordx4 v158, s[98:99]
	s_mov_b32 m0, s3
	s_nop 0
	global_load_lds_dwordx4 v154, s[38:39]
	s_add_i32 m0, s3, 0x2000
	s_nop 0
	global_load_lds_dwordx4 v158, s[38:39]
	s_mov_b32 m0, s56
	s_nop 0
	global_load_lds_dwordx4 v152, s[100:101]
	s_mov_b32 m0, s57
	s_nop 0
	global_load_lds_dwordx4 v156, s[100:101]
	s_waitcnt vmcnt(8)
	s_waitcnt lgkmcnt(0)
	s_setprio 1
	s_barrier
	v_mfma_f32_16x16x32_bf16 v[60:63], v[128:131], v[174:177], v[60:63]
	v_mfma_f32_16x16x32_bf16 v[56:59], v[136:139], v[174:177], v[56:59]
	v_mfma_f32_16x16x32_bf16 v[44:47], v[128:131], v[194:197], v[44:47]
	v_mfma_f32_16x16x32_bf16 v[40:43], v[136:139], v[194:197], v[40:43]
	v_mfma_f32_16x16x32_bf16 v[28:31], v[128:131], v[202:205], v[28:31]
	v_mfma_f32_16x16x32_bf16 v[24:27], v[136:139], v[202:205], v[24:27]
	v_mfma_f32_16x16x32_bf16 v[12:15], v[128:131], v[210:213], v[12:15]
	v_mfma_f32_16x16x32_bf16 v[8:11], v[136:139], v[210:213], v[8:11]
	v_mfma_f32_16x16x32_bf16 v[60:63], v[132:135], v[178:181], v[60:63]
	v_mfma_f32_16x16x32_bf16 v[56:59], v[140:143], v[178:181], v[56:59]
	v_mfma_f32_16x16x32_bf16 v[44:47], v[132:135], v[198:201], v[44:47]
	v_mfma_f32_16x16x32_bf16 v[40:43], v[140:143], v[198:201], v[40:43]
	v_mfma_f32_16x16x32_bf16 v[28:31], v[132:135], v[206:209], v[28:31]
	v_mfma_f32_16x16x32_bf16 v[24:27], v[140:143], v[206:209], v[24:27]
	v_mfma_f32_16x16x32_bf16 v[12:15], v[132:135], v[214:217], v[12:15]
	v_mfma_f32_16x16x32_bf16 v[8:11], v[140:143], v[214:217], v[8:11]
	s_setprio 0
	s_setprio 1
	v_mfma_f32_16x16x32_bf16 v[52:55], v[144:147], v[174:177], v[52:55]
	v_mfma_f32_16x16x32_bf16 v[48:51], v[166:169], v[174:177], v[48:51]
	v_mfma_f32_16x16x32_bf16 v[36:39], v[144:147], v[194:197], v[36:39]
	v_mfma_f32_16x16x32_bf16 v[32:35], v[166:169], v[194:197], v[32:35]
	v_mfma_f32_16x16x32_bf16 v[20:23], v[144:147], v[202:205], v[20:23]
	v_mfma_f32_16x16x32_bf16 v[16:19], v[166:169], v[202:205], v[16:19]
	v_mfma_f32_16x16x32_bf16 v[4:7], v[144:147], v[210:213], v[4:7]
	v_mfma_f32_16x16x32_bf16 v[0:3], v[166:169], v[210:213], v[0:3]
	v_mfma_f32_16x16x32_bf16 v[52:55], v[148:151], v[178:181], v[52:55]
	v_mfma_f32_16x16x32_bf16 v[48:51], v[170:173], v[178:181], v[48:51]
	v_mfma_f32_16x16x32_bf16 v[36:39], v[148:151], v[198:201], v[36:39]
	v_mfma_f32_16x16x32_bf16 v[32:35], v[170:173], v[198:201], v[32:35]
	v_mfma_f32_16x16x32_bf16 v[20:23], v[148:151], v[206:209], v[20:23]
	v_mfma_f32_16x16x32_bf16 v[16:19], v[170:173], v[206:209], v[16:19]
	v_mfma_f32_16x16x32_bf16 v[4:7], v[148:151], v[214:217], v[4:7]
	v_mfma_f32_16x16x32_bf16 v[0:3], v[170:173], v[214:217], v[0:3]
	s_setprio 0
	s_barrier
	s_add_i32 s1, s1, 2
	s_add_u32 s4, s4, 0x100
	s_addc_u32 s5, s5, 0
	s_cmpk_gt_u32 s1, 0x53
	s_mov_b64 s[38:39], s[40:41]
	s_cbranch_scc0 .LBB0_876
	s_and_b64 vcc, exec, s[26:27]
	s_cbranch_vccz .LBB0_879
	s_barrier

	.amdhsa_kernel _Z10fwd_kernelILi255ELi0ELi8EEv4Args
		.amdhsa_group_segment_fixed_size 0
		.amdhsa_private_segment_fixed_size 0
		.amdhsa_kernarg_size 496
		.amdhsa_user_sgpr_count 2
		.amdhsa_user_sgpr_dispatch_ptr 0
		.amdhsa_user_sgpr_queue_ptr 0
		.amdhsa_user_sgpr_kernarg_segment_ptr 1
		.amdhsa_user_sgpr_dispatch_id 0
		.amdhsa_user_sgpr_kernarg_preload_length 0
		.amdhsa_user_sgpr_kernarg_preload_offset 0
		.amdhsa_user_sgpr_private_segment_size 0
		.amdhsa_uses_dynamic_stack 0
		.amdhsa_enable_private_segment 0
		.amdhsa_system_sgpr_workgroup_id_x 1
		.amdhsa_system_sgpr_workgroup_id_y 0
		.amdhsa_system_sgpr_workgroup_id_z 0
		.amdhsa_system_sgpr_workgroup_info 0
		.amdhsa_system_vgpr_workitem_id 0
		.amdhsa_next_free_vgpr 256
		.amdhsa_next_free_sgpr 102
		.amdhsa_accum_offset 256
		.amdhsa_reserve_vcc 1
		.amdhsa_float_round_mode_32 0
		.amdhsa_float_round_mode_16_64 0
		.amdhsa_float_denorm_mode_32 3
		.amdhsa_float_denorm_mode_16_64 3
		.amdhsa_dx10_clamp 1
		.amdhsa_ieee_mode 1
		.amdhsa_fp16_overflow 0
		.amdhsa_tg_split 0
		.amdhsa_exception_fp_ieee_invalid_op 0
		.amdhsa_exception_fp_denorm_src 0
		.amdhsa_exception_fp_ieee_div_zero 0
		.amdhsa_exception_fp_ieee_overflow 0
		.amdhsa_exception_fp_ieee_underflow 0
		.amdhsa_exception_fp_ieee_inexact 0
		.amdhsa_exception_int_div_zero 0
	.end_amdhsa_kernel

amdhsa.kernels:
  - .agpr_count:     0
    .args:
      - .offset:         0
        .size:           240
        .value_kind:     by_value
      - .offset:         240
        .size:           4
        .value_kind:     hidden_block_count_x
      - .offset:         244
        .size:           4
        .value_kind:     hidden_block_count_y
      - .offset:         248
        .size:           4
        .value_kind:     hidden_block_count_z
      - .offset:         252
        .size:           2
        .value_kind:     hidden_group_size_x
      - .offset:         254
        .size:           2
        .value_kind:     hidden_group_size_y
      - .offset:         256
        .size:           2
        .value_kind:     hidden_group_size_z
      - .offset:         258
        .size:           2
        .value_kind:     hidden_remainder_x
      - .offset:         260
        .size:           2
        .value_kind:     hidden_remainder_y
      - .offset:         262
        .size:           2
        .value_kind:     hidden_remainder_z
      - .offset:         280
        .size:           8
        .value_kind:     hidden_global_offset_x
      - .offset:         288
        .size:           8
        .value_kind:     hidden_global_offset_y
      - .offset:         296
        .size:           8
        .value_kind:     hidden_global_offset_z
      - .offset:         304
        .size:           2
        .value_kind:     hidden_grid_dims
      - .offset:         360
        .size:           4
        .value_kind:     hidden_dynamic_lds_size
    .group_segment_fixed_size: 0
    .kernarg_segment_align: 8
    .kernarg_segment_size: 496
    .language:       OpenCL C
    .language_version:
      - 2
      - 0
    .max_flat_workgroup_size: 512
    .name:           _Z10fwd_kernelILi255ELi0ELi8EEv4Args
    .private_segment_fixed_size: 0
    .sgpr_count:     108
    .sgpr_spill_count: 15
    .symbol:         _Z10fwd_kernelILi255ELi0ELi8EEv4Args.kd
    .uniform_work_group_size: 1
    .uses_dynamic_stack: false
    .vgpr_count:     256
    .vgpr_spill_count: 0
    .wavefront_size: 64
